# EpiUp prompt-tile epilogue in registers: conv3+gelu on f32 accumulators via DPP row shifts, LDS halo for cross-wave rows, no L2 scratch round trip
# speedup vs baseline: 1.0316x; 1.0316x over previous
.LBB0_1153:
	s_cmp_lt_i32 s2, 64
	s_cbranch_scc1 .Lepi9_prompt
	s_lshl_b32 s10, s10, 7
	v_mov_b32_e32 v166, v192
	s_ashr_i32 s11, s10, 31
	s_lshl_b64 s[52:53], s[10:11], 2
	v_lshrrev_b32_e32 v128, 1, v166
	v_and_b32_e32 v172, 0x78, v128
	s_add_u32 s52, s16, s52
	s_addc_u32 s53, s17, s53
	v_lshlrev_b32_e32 v152, 2, v172
	v_lshl_add_u64 v[140:141], s[52:53], 0, v[152:153]
	global_load_dwordx4 v[128:131], v152, s[52:53] offset:16
	global_load_dwordx4 v[136:139], v152, s[52:53]
	s_mov_b64 s[52:53], 0x2c00
	v_add_co_u32_e32 v132, vcc, s69, v140
	s_mov_b32 s3, 0xffffc0
	s_nop 0
	v_addc_co_u32_e32 v133, vcc, 0, v141, vcc
	v_lshl_add_u64 v[140:141], v[140:141], 0, s[52:53]
	global_load_dwordx4 v[132:135], v[132:133], off offset:3072
	v_and_b32_e32 v152, 15, v166
	global_load_dwordx4 v[140:143], v[140:141], off offset:16
	v_lshrrev_b32_e32 v166, 2, v166
	v_and_or_b32 v152, v166, s3, v152
	v_lshlrev_b32_e32 v166, 8, v152
	v_ashrrev_i32_e32 v167, 31, v166
	v_lshlrev_b32_e32 v152, 1, v172
	v_lshl_add_u64 v[172:173], v[166:167], 1, s[22:23]
	v_lshl_add_u64 v[172:173], v[172:173], 0, v[152:153]
	s_waitcnt vmcnt(0)
	v_pk_add_f32 v[174:175], v[122:123], v[130:131]
	v_pk_add_f32 v[126:127], v[126:127], v[138:139]
	v_pk_add_f32 v[124:125], v[124:125], v[136:137]
	v_pk_add_f32 v[122:123], v[120:121], v[128:129]
	v_cvt_pk_bf16_f32 v120, v124, v125
	v_cvt_pk_bf16_f32 v121, v126, v127
	v_cvt_pk_bf16_f32 v122, v122, v123
	v_cvt_pk_bf16_f32 v123, v174, v175
	global_store_dwordx4 v[172:173], v[120:123], off
	v_pk_add_f32 v[118:119], v[118:119], v[134:135]
	v_pk_add_f32 v[116:117], v[116:117], v[132:133]
	v_pk_add_f32 v[120:121], v[106:107], v[142:143]
	v_pk_add_f32 v[106:107], v[104:105], v[140:141]
	v_cvt_pk_bf16_f32 v104, v116, v117
	v_cvt_pk_bf16_f32 v105, v118, v119
	v_cvt_pk_bf16_f32 v106, v106, v107
	v_cvt_pk_bf16_f32 v107, v120, v121
	global_store_dwordx4 v[172:173], v[104:107], off offset:256
	s_nop 1
	v_pk_add_f32 v[106:107], v[114:115], v[138:139]
	v_pk_add_f32 v[104:105], v[112:113], v[136:137]
	v_pk_add_f32 v[108:109], v[108:109], v[128:129]
	v_pk_add_f32 v[110:111], v[110:111], v[130:131]
	v_cvt_pk_bf16_f32 v104, v104, v105
	v_cvt_pk_bf16_f32 v105, v106, v107
	v_cvt_pk_bf16_f32 v106, v108, v109
	v_add_co_u32_e32 v108, vcc, s69, v172
	v_cvt_pk_bf16_f32 v107, v110, v111
	s_nop 0
	v_addc_co_u32_e32 v109, vcc, 0, v173, vcc
	global_store_dwordx4 v[108:109], v[104:107], off
	v_pk_add_f32 v[98:99], v[98:99], v[134:135]
	v_pk_add_f32 v[96:97], v[96:97], v[132:133]
	v_pk_add_f32 v[104:105], v[90:91], v[142:143]
	v_pk_add_f32 v[90:91], v[88:89], v[140:141]
	v_cvt_pk_bf16_f32 v88, v96, v97
	v_cvt_pk_bf16_f32 v89, v98, v99
	v_cvt_pk_bf16_f32 v90, v90, v91
	v_cvt_pk_bf16_f32 v91, v104, v105
	global_store_dwordx4 v[108:109], v[88:91], off offset:256
	s_nop 1
	v_pk_add_f32 v[90:91], v[102:103], v[138:139]
	v_pk_add_f32 v[88:89], v[100:101], v[136:137]
	v_pk_add_f32 v[92:93], v[92:93], v[128:129]
	s_movk_i32 s3, 0x4000
	v_pk_add_f32 v[94:95], v[94:95], v[130:131]
	v_cvt_pk_bf16_f32 v88, v88, v89
	v_cvt_pk_bf16_f32 v89, v90, v91
	v_cvt_pk_bf16_f32 v90, v92, v93
	v_add_co_u32_e32 v92, vcc, s3, v172
	v_cvt_pk_bf16_f32 v91, v94, v95
	s_nop 0
	v_addc_co_u32_e32 v93, vcc, 0, v173, vcc
	global_store_dwordx4 v[92:93], v[88:91], off
	v_pk_add_f32 v[82:83], v[82:83], v[134:135]
	v_pk_add_f32 v[80:81], v[80:81], v[132:133]
	v_pk_add_f32 v[88:89], v[74:75], v[142:143]
	v_pk_add_f32 v[74:75], v[72:73], v[140:141]
	v_cvt_pk_bf16_f32 v72, v80, v81
	v_cvt_pk_bf16_f32 v73, v82, v83
	v_cvt_pk_bf16_f32 v74, v74, v75
	v_cvt_pk_bf16_f32 v75, v88, v89
	global_store_dwordx4 v[92:93], v[72:75], off offset:256
	s_nop 1
	v_pk_add_f32 v[74:75], v[86:87], v[138:139]
	v_pk_add_f32 v[72:73], v[84:85], v[136:137]
	v_pk_add_f32 v[76:77], v[76:77], v[128:129]
	s_movk_i32 s3, 0x6000
	v_pk_add_f32 v[78:79], v[78:79], v[130:131]
	v_cvt_pk_bf16_f32 v72, v72, v73
	v_cvt_pk_bf16_f32 v73, v74, v75
	v_cvt_pk_bf16_f32 v74, v76, v77
	v_add_co_u32_e32 v76, vcc, s3, v172
	v_cvt_pk_bf16_f32 v75, v78, v79
	s_nop 0
	v_addc_co_u32_e32 v77, vcc, 0, v173, vcc
	global_store_dwordx4 v[76:77], v[72:75], off
	v_pk_add_f32 v[70:71], v[70:71], v[134:135]
	v_pk_add_f32 v[68:69], v[68:69], v[132:133]
	v_pk_add_f32 v[72:73], v[66:67], v[142:143]
	v_pk_add_f32 v[66:67], v[64:65], v[140:141]
	v_cvt_pk_bf16_f32 v64, v68, v69
	v_cvt_pk_bf16_f32 v65, v70, v71
	v_cvt_pk_bf16_f32 v66, v66, v67
	v_cvt_pk_bf16_f32 v67, v72, v73
	global_store_dwordx4 v[76:77], v[64:67], off offset:256
	s_nop 1
	v_add_u32_e32 v64, 0x8000, v166
	v_ashrrev_i32_e32 v65, 31, v64
	v_pk_add_f32 v[60:61], v[60:61], v[136:137]
	v_pk_add_f32 v[62:63], v[62:63], v[138:139]
	v_pk_add_f32 v[66:67], v[58:59], v[130:131]
	v_pk_add_f32 v[58:59], v[56:57], v[128:129]
	v_cvt_pk_bf16_f32 v56, v60, v61
	v_lshl_add_u64 v[60:61], v[64:65], 1, s[22:23]
	v_cvt_pk_bf16_f32 v57, v62, v63
	v_cvt_pk_bf16_f32 v58, v58, v59
	v_cvt_pk_bf16_f32 v59, v66, v67
	v_lshl_add_u64 v[60:61], v[60:61], 0, v[152:153]
	global_store_dwordx4 v[60:61], v[56:59], off
	v_pk_add_f32 v[50:51], v[50:51], v[134:135]
	v_pk_add_f32 v[48:49], v[48:49], v[132:133]
	v_pk_add_f32 v[56:57], v[42:43], v[142:143]
	v_pk_add_f32 v[42:43], v[40:41], v[140:141]
	v_cvt_pk_bf16_f32 v40, v48, v49
	v_cvt_pk_bf16_f32 v41, v50, v51
	v_cvt_pk_bf16_f32 v42, v42, v43
	v_cvt_pk_bf16_f32 v43, v56, v57
	global_store_dwordx4 v[60:61], v[40:43], off offset:256
	v_add_u32_e32 v48, 0x9000, v166
	v_ashrrev_i32_e32 v49, 31, v48
	v_pk_add_f32 v[42:43], v[54:55], v[138:139]
	v_pk_add_f32 v[40:41], v[52:53], v[136:137]
	v_pk_add_f32 v[44:45], v[44:45], v[128:129]
	v_pk_add_f32 v[46:47], v[46:47], v[130:131]
	v_cvt_pk_bf16_f32 v40, v40, v41
	v_cvt_pk_bf16_f32 v41, v42, v43
	v_cvt_pk_bf16_f32 v42, v44, v45
	v_lshl_add_u64 v[44:45], v[48:49], 1, s[22:23]
	v_cvt_pk_bf16_f32 v43, v46, v47
	v_lshl_add_u64 v[44:45], v[44:45], 0, v[152:153]
	global_store_dwordx4 v[44:45], v[40:43], off
	v_pk_add_f32 v[34:35], v[34:35], v[134:135]
	v_pk_add_f32 v[32:33], v[32:33], v[132:133]
	v_pk_add_f32 v[40:41], v[26:27], v[142:143]
	v_pk_add_f32 v[26:27], v[24:25], v[140:141]
	v_cvt_pk_bf16_f32 v24, v32, v33
	v_cvt_pk_bf16_f32 v25, v34, v35
	v_cvt_pk_bf16_f32 v26, v26, v27
	v_cvt_pk_bf16_f32 v27, v40, v41
	global_store_dwordx4 v[44:45], v[24:27], off offset:256
	v_add_u32_e32 v32, 0xa000, v166
	v_ashrrev_i32_e32 v33, 31, v32
	v_pk_add_f32 v[26:27], v[38:39], v[138:139]
	v_pk_add_f32 v[24:25], v[36:37], v[136:137]
	v_pk_add_f32 v[28:29], v[28:29], v[128:129]
	v_pk_add_f32 v[30:31], v[30:31], v[130:131]
	v_cvt_pk_bf16_f32 v24, v24, v25
	v_cvt_pk_bf16_f32 v25, v26, v27
	v_cvt_pk_bf16_f32 v26, v28, v29
	v_lshl_add_u64 v[28:29], v[32:33], 1, s[22:23]
	v_cvt_pk_bf16_f32 v27, v30, v31
	v_lshl_add_u64 v[28:29], v[28:29], 0, v[152:153]
	global_store_dwordx4 v[28:29], v[24:27], off
	v_pk_add_f32 v[18:19], v[18:19], v[134:135]
	v_pk_add_f32 v[16:17], v[16:17], v[132:133]
	v_pk_add_f32 v[24:25], v[10:11], v[142:143]
	v_pk_add_f32 v[10:11], v[8:9], v[140:141]
	v_cvt_pk_bf16_f32 v8, v16, v17
	v_cvt_pk_bf16_f32 v9, v18, v19
	v_cvt_pk_bf16_f32 v10, v10, v11
	v_cvt_pk_bf16_f32 v11, v24, v25
	global_store_dwordx4 v[28:29], v[8:11], off offset:256
	v_add_u32_e32 v16, 0xb000, v166
	v_ashrrev_i32_e32 v17, 31, v16
	v_pk_add_f32 v[10:11], v[22:23], v[138:139]
	v_pk_add_f32 v[8:9], v[20:21], v[136:137]
	v_pk_add_f32 v[12:13], v[12:13], v[128:129]
	v_pk_add_f32 v[14:15], v[14:15], v[130:131]
	v_cvt_pk_bf16_f32 v8, v8, v9
	v_cvt_pk_bf16_f32 v9, v10, v11
	v_cvt_pk_bf16_f32 v10, v12, v13
	v_lshl_add_u64 v[12:13], v[16:17], 1, s[22:23]
	v_cvt_pk_bf16_f32 v11, v14, v15
	v_lshl_add_u64 v[12:13], v[12:13], 0, v[152:153]
	global_store_dwordx4 v[12:13], v[8:11], off
	v_pk_add_f32 v[6:7], v[6:7], v[134:135]
	v_pk_add_f32 v[4:5], v[4:5], v[132:133]
	v_pk_add_f32 v[8:9], v[2:3], v[142:143]
	v_pk_add_f32 v[2:3], v[0:1], v[140:141]
	v_cvt_pk_bf16_f32 v0, v4, v5
	v_cvt_pk_bf16_f32 v1, v6, v7
	v_cvt_pk_bf16_f32 v2, v2, v3
	v_cvt_pk_bf16_f32 v3, v8, v9
	global_store_dwordx4 v[12:13], v[0:3], off offset:256
	v_or_b32_e32 v18, s10, v154
	v_ashrrev_i32_e32 v19, 31, v18
	v_lshlrev_b64 v[0:1], 2, v[18:19]
	s_waitcnt vmcnt(0)
	s_barrier
	v_lshl_add_u64 v[2:3], s[4:5], 0, v[0:1]
	v_lshl_add_u64 v[4:5], s[30:31], 0, v[0:1]
	v_lshl_add_u64 v[6:7], s[18:19], 0, v[0:1]
	v_lshl_add_u64 v[8:9], s[34:35], 0, v[0:1]
	v_lshl_add_u64 v[10:11], s[36:37], 0, v[0:1]
	v_lshl_add_u64 v[12:13], s[38:39], 0, v[0:1]
	global_load_dwordx2 v[2:3], v[2:3], off
	s_nop 0
	global_load_dwordx2 v[4:5], v[4:5], off
	s_nop 0
	global_load_dwordx2 v[6:7], v[6:7], off
	s_nop 0
	global_load_dwordx2 v[8:9], v[8:9], off
	s_nop 0
	global_load_dwordx2 v[10:11], v[10:11], off
	s_nop 0
	global_load_dwordx2 v[12:13], v[12:13], off
	v_lshl_add_u64 v[14:15], s[40:41], 0, v[0:1]
	v_lshl_add_u64 v[16:17], s[42:43], 0, v[0:1]
	global_load_dwordx2 v[14:15], v[14:15], off
	s_nop 0
	global_load_dwordx2 v[16:17], v[16:17], off
	s_mov_b64 s[10:11], -1

.Lepi9_prompt:
	v_and_b32_e32 v234, 0xf, v192
	v_cmp_gt_u32_e64 s[52:53], 2, v234
	v_cmp_lt_u32_e64 s[54:55], 13, v234
	v_readfirstlane_b32 s33, v192
	v_bfe_u32 v241, v192, 4, 2
	v_bfe_u32 v242, v192, 6, 2
	s_lshr_b32 s33, s33, 8
	v_lshlrev_b32_e32 v240, 0x5, v242
	v_lshl_add_u32 v240, v241, 3, v240
	s_lshl_b32 s11, s10, 7
	v_add_u32_e32 v243, s11, v240
	v_lshlrev_b32_e32 v243, 0x2, v243
	v_lshrrev_b32_e32 v237, 0x6, v192
	v_lshlrev_b32_e32 v237, 0xa, v237
	v_bfe_u32 v238, v192, 4, 2
	v_lshl_add_u32 v237, v238, 7, v237
	v_lshl_add_u32 v237, v234, 6, v237
	v_add_u32_e32 v237, 0x1fc80, v237
	global_load_dwordx4 v[226:229], v243, s[16:17]
	v_add_u32_e32 v242, 0x2c00, v243
	global_load_dwordx4 v[230:233], v242, s[16:17]
	global_load_dwordx4 v[206:209], v243, s[4:5]
	global_load_dwordx4 v[222:225], v243, s[30:31]
	global_load_dwordx4 v[194:197], v243, s[18:19]
	global_load_dwordx4 v[198:201], v243, s[34:35]
	global_load_dwordx4 v[202:205], v243, s[36:37]
	global_load_dwordx4 v[210:213], v243, s[38:39]
	global_load_dwordx4 v[214:217], v243, s[40:41]
	global_load_dwordx4 v[218:221], v243, s[42:43]
	s_mov_b64 exec, s[54:55]
	ds_write_b128 v237, v[84:87]
	ds_write_b128 v237, v[76:79] offset:16
	ds_write_b128 v237, v[68:71] offset:32
	ds_write_b128 v237, v[64:67] offset:48
	ds_write_b128 v237, v[20:23] offset:512
	ds_write_b128 v237, v[12:15] offset:528
	ds_write_b128 v237, v[4:7] offset:544
	ds_write_b128 v237, v[0:3] offset:560
	s_mov_b64 exec, -1
	v_xor_b32_e32 v238, 0x1000, v237
	s_lshl_b32 s3, s33, 9
	v_add_u32_e32 v239, s3, v238
	v_lshrrev_b32_e32 v235, 0x8, v192
	v_lshl_add_u32 v235, v235, 6, v234
	v_mul_u32_u24_e32 v235, 0x1600, v235
	v_lshl_add_u32 v235, v240, 1, v235
	s_mul_i32 s3, s2, 0x160000
	s_add_u32 s56, s24, s3
	s_addc_u32 s57, s25, 0
	s_lshl_b32 s3, s10, 8
	s_add_u32 s56, s56, s3
	s_addc_u32 s57, s57, 0
	v_mul_u32_u24_e32 v236, 0x2c00, v234
	v_lshl_add_u32 v236, v240, 1, v236
	s_waitcnt lgkmcnt(0)
	s_barrier
	ds_read_b128 v[128:131], v238
	ds_read_b128 v[132:135], v238 offset:32
	ds_read_b128 v[136:139], v239
	ds_read_b128 v[140:143], v239 offset:32
	s_waitcnt vmcnt(0)
	s_lshl_b32 s3, s2, 2
	s_add_u32 s3, s3, 2
	s_mul_i32 s3, s3, 0x2c00
	s_add_u32 s58, s14, s3
	s_addc_u32 s59, s15, 0
	s_lshl_b32 s3, s10, 8
	s_add_u32 s58, s58, s3
	s_addc_u32 s59, s59, 0
	s_cmp_lg_u32 s33, 0
	s_cbranch_scc1 .Lepi9_wr1_1
	s_mov_b64 exec, s[52:53]
	v_add_f32_e32 v184, v124, v226
	v_add_f32_e32 v185, v125, v227
	v_add_f32_e32 v186, v126, v228
	v_add_f32_e32 v187, v127, v229
	v_cvt_pk_bf16_f32 v184, v184, v185
	v_cvt_pk_bf16_f32 v185, v186, v187
	global_store_dwordx2 v236, v[184:185], s[58:59]
	v_add_f32_e32 v188, v116, v230
	v_add_f32_e32 v189, v117, v231
	v_add_f32_e32 v190, v118, v232
	v_add_f32_e32 v191, v119, v233
	v_cvt_pk_bf16_f32 v188, v188, v189
	v_cvt_pk_bf16_f32 v189, v190, v191
	v_add_u32_e32 v241, 0x1600, v236
	global_store_dwordx2 v241, v[188:189], s[58:59]
	s_mov_b64 exec, -1
	s_branch .Lepi9_wrend_1
.Lepi9_wr1_1:
	s_mov_b64 exec, s[54:55]
	v_add_u32_e32 v242, 0xfffdf000, v236
	v_add_f32_e32 v184, v20, v226
	v_add_f32_e32 v185, v21, v227
	v_add_f32_e32 v186, v22, v228
	v_add_f32_e32 v187, v23, v229
	v_cvt_pk_bf16_f32 v184, v184, v185
	v_cvt_pk_bf16_f32 v185, v186, v187
	global_store_dwordx2 v242, v[184:185], s[58:59]
	v_add_f32_e32 v188, v4, v230
	v_add_f32_e32 v189, v5, v231
	v_add_f32_e32 v190, v6, v232
	v_add_f32_e32 v191, v7, v233
	v_cvt_pk_bf16_f32 v188, v188, v189
	v_cvt_pk_bf16_f32 v189, v190, v191
	v_add_u32_e32 v241, 0x1600, v242
	global_store_dwordx2 v241, v[188:189], s[58:59]
	s_mov_b64 exec, -1
.Lepi9_wrend_1:
	v_add_f32_e32 v180, v194, v198
	v_add_f32_e32 v181, v195, v199
	v_add_f32_e32 v182, v196, v200
	v_add_f32_e32 v183, v197, v201
	v_add_f32_e32 v180, v180, v202
	v_add_f32_e32 v181, v181, v203
	v_add_f32_e32 v182, v182, v204
	v_add_f32_e32 v183, v183, v205
	v_fma_f32 v206, v226, v180, v206
	v_fma_f32 v207, v227, v181, v207
	v_fma_f32 v208, v228, v182, v208
	v_fma_f32 v209, v229, v183, v209
	v_add_f32_e32 v180, v210, v214
	v_add_f32_e32 v181, v211, v215
	v_add_f32_e32 v182, v212, v216
	v_add_f32_e32 v183, v213, v217
	v_add_f32_e32 v180, v180, v218
	v_add_f32_e32 v181, v181, v219
	v_add_f32_e32 v182, v182, v220
	v_add_f32_e32 v183, v183, v221
	v_fma_f32 v222, v230, v180, v222
	v_fma_f32 v223, v231, v181, v223
	v_fma_f32 v224, v232, v182, v224
	v_fma_f32 v225, v233, v183, v225
	s_waitcnt lgkmcnt(0)
	v_fma_f32 v172, v202, v84, v206
	v_fma_f32 v173, v203, v85, v207
	v_fma_f32 v174, v204, v86, v208
	v_fma_f32 v175, v205, v87, v209
	v_fma_f32 v176, v218, v68, v222
	v_fma_f32 v177, v219, v69, v223
	v_fma_f32 v178, v220, v70, v224
	v_fma_f32 v179, v221, v71, v225
	v_fmac_f32_dpp v172, v84, v198 row_shr:1 row_mask:0xf bank_mask:0xf
	v_fmac_f32_dpp v173, v85, v199 row_shr:1 row_mask:0xf bank_mask:0xf
	v_fmac_f32_dpp v174, v86, v200 row_shr:1 row_mask:0xf bank_mask:0xf
	v_fmac_f32_dpp v175, v87, v201 row_shr:1 row_mask:0xf bank_mask:0xf
	v_fmac_f32_dpp v176, v68, v214 row_shr:1 row_mask:0xf bank_mask:0xf
	v_fmac_f32_dpp v177, v69, v215 row_shr:1 row_mask:0xf bank_mask:0xf
	v_fmac_f32_dpp v178, v70, v216 row_shr:1 row_mask:0xf bank_mask:0xf
	v_fmac_f32_dpp v179, v71, v217 row_shr:1 row_mask:0xf bank_mask:0xf
	v_fmac_f32_dpp v172, v84, v194 row_shr:2 row_mask:0xf bank_mask:0xf
	v_fmac_f32_dpp v173, v85, v195 row_shr:2 row_mask:0xf bank_mask:0xf
	v_fmac_f32_dpp v174, v86, v196 row_shr:2 row_mask:0xf bank_mask:0xf
	v_fmac_f32_dpp v175, v87, v197 row_shr:2 row_mask:0xf bank_mask:0xf
	v_fmac_f32_dpp v176, v68, v210 row_shr:2 row_mask:0xf bank_mask:0xf
	v_fmac_f32_dpp v177, v69, v211 row_shr:2 row_mask:0xf bank_mask:0xf
	v_fmac_f32_dpp v178, v70, v212 row_shr:2 row_mask:0xf bank_mask:0xf
	v_fmac_f32_dpp v179, v71, v213 row_shr:2 row_mask:0xf bank_mask:0xf
	v_fmac_f32_dpp v172, v100, v198 row_shl:15 row_mask:0xf bank_mask:0xf
	v_fmac_f32_dpp v173, v101, v199 row_shl:15 row_mask:0xf bank_mask:0xf
	v_fmac_f32_dpp v174, v102, v200 row_shl:15 row_mask:0xf bank_mask:0xf
	v_fmac_f32_dpp v175, v103, v201 row_shl:15 row_mask:0xf bank_mask:0xf
	v_fmac_f32_dpp v176, v80, v214 row_shl:15 row_mask:0xf bank_mask:0xf
	v_fmac_f32_dpp v177, v81, v215 row_shl:15 row_mask:0xf bank_mask:0xf
	v_fmac_f32_dpp v178, v82, v216 row_shl:15 row_mask:0xf bank_mask:0xf
	v_fmac_f32_dpp v179, v83, v217 row_shl:15 row_mask:0xf bank_mask:0xf
	v_fmac_f32_dpp v172, v100, v194 row_shl:14 row_mask:0xf bank_mask:0xf
	v_fmac_f32_dpp v173, v101, v195 row_shl:14 row_mask:0xf bank_mask:0xf
	v_fmac_f32_dpp v174, v102, v196 row_shl:14 row_mask:0xf bank_mask:0xf
	v_fmac_f32_dpp v175, v103, v197 row_shl:14 row_mask:0xf bank_mask:0xf
	v_fmac_f32_dpp v176, v80, v210 row_shl:14 row_mask:0xf bank_mask:0xf
	v_fmac_f32_dpp v177, v81, v211 row_shl:14 row_mask:0xf bank_mask:0xf
	v_fmac_f32_dpp v178, v82, v212 row_shl:14 row_mask:0xf bank_mask:0xf
	v_fmac_f32_dpp v179, v83, v213 row_shl:14 row_mask:0xf bank_mask:0xf
	v_mul_f32_e32 v180, 0x3d372713, v172
	v_mul_f32_e32 v181, 0x3d372713, v173
	v_mul_f32_e32 v182, 0x3d372713, v174
	v_mul_f32_e32 v183, 0x3d372713, v175
	v_mul_f32_e32 v180, v172, v180
	v_mul_f32_e32 v181, v173, v181
	v_mul_f32_e32 v182, v174, v182
	v_mul_f32_e32 v183, v175, v183
	v_fma_f32 v180, v172, v180, v172
	v_fma_f32 v181, v173, v181, v173
	v_fma_f32 v182, v174, v182, v174
	v_fma_f32 v183, v175, v183, v175
	v_mul_f32_e32 v180, 0xc0135761, v180
	v_mul_f32_e32 v181, 0xc0135761, v181
	v_mul_f32_e32 v182, 0xc0135761, v182
	v_mul_f32_e32 v183, 0xc0135761, v183
	v_exp_f32_e32 v180, v180
	v_exp_f32_e32 v181, v181
	v_exp_f32_e32 v182, v182
	v_exp_f32_e32 v183, v183
	v_add_f32_e32 v180, 1.0, v180
	v_add_f32_e32 v181, 1.0, v181
	v_add_f32_e32 v182, 1.0, v182
	v_add_f32_e32 v183, 1.0, v183
	v_rcp_f32_e32 v180, v180
	v_rcp_f32_e32 v181, v181
	v_rcp_f32_e32 v182, v182
	v_rcp_f32_e32 v183, v183
	v_mul_f32_e32 v172, v172, v180
	v_mul_f32_e32 v173, v173, v181
	v_mul_f32_e32 v174, v174, v182
	v_mul_f32_e32 v175, v175, v183
	v_mul_f32_e32 v172, v172, v176
	v_mul_f32_e32 v173, v173, v177
	v_mul_f32_e32 v174, v174, v178
	v_mul_f32_e32 v175, v175, v179
	v_cvt_pk_bf16_f32 v84, v172, v173
	v_cvt_pk_bf16_f32 v85, v174, v175
	v_fma_f32 v172, v202, v100, v206
	v_fma_f32 v173, v203, v101, v207
	v_fma_f32 v174, v204, v102, v208
	v_fma_f32 v175, v205, v103, v209
	v_fma_f32 v176, v218, v80, v222
	v_fma_f32 v177, v219, v81, v223
	v_fma_f32 v178, v220, v82, v224
	v_fma_f32 v179, v221, v83, v225
	v_fmac_f32_dpp v172, v100, v198 row_shr:1 row_mask:0xf bank_mask:0xf
	v_fmac_f32_dpp v173, v101, v199 row_shr:1 row_mask:0xf bank_mask:0xf
	v_fmac_f32_dpp v174, v102, v200 row_shr:1 row_mask:0xf bank_mask:0xf
	v_fmac_f32_dpp v175, v103, v201 row_shr:1 row_mask:0xf bank_mask:0xf
	v_fmac_f32_dpp v176, v80, v214 row_shr:1 row_mask:0xf bank_mask:0xf
	v_fmac_f32_dpp v177, v81, v215 row_shr:1 row_mask:0xf bank_mask:0xf
	v_fmac_f32_dpp v178, v82, v216 row_shr:1 row_mask:0xf bank_mask:0xf
	v_fmac_f32_dpp v179, v83, v217 row_shr:1 row_mask:0xf bank_mask:0xf
	v_fmac_f32_dpp v172, v100, v194 row_shr:2 row_mask:0xf bank_mask:0xf
	v_fmac_f32_dpp v173, v101, v195 row_shr:2 row_mask:0xf bank_mask:0xf
	v_fmac_f32_dpp v174, v102, v196 row_shr:2 row_mask:0xf bank_mask:0xf
	v_fmac_f32_dpp v175, v103, v197 row_shr:2 row_mask:0xf bank_mask:0xf
	v_fmac_f32_dpp v176, v80, v210 row_shr:2 row_mask:0xf bank_mask:0xf
	v_fmac_f32_dpp v177, v81, v211 row_shr:2 row_mask:0xf bank_mask:0xf
	v_fmac_f32_dpp v178, v82, v212 row_shr:2 row_mask:0xf bank_mask:0xf
	v_fmac_f32_dpp v179, v83, v213 row_shr:2 row_mask:0xf bank_mask:0xf
	v_fmac_f32_dpp v172, v112, v198 row_shl:15 row_mask:0xf bank_mask:0xf
	v_fmac_f32_dpp v173, v113, v199 row_shl:15 row_mask:0xf bank_mask:0xf
	v_fmac_f32_dpp v174, v114, v200 row_shl:15 row_mask:0xf bank_mask:0xf
	v_fmac_f32_dpp v175, v115, v201 row_shl:15 row_mask:0xf bank_mask:0xf
	v_fmac_f32_dpp v176, v96, v214 row_shl:15 row_mask:0xf bank_mask:0xf
	v_fmac_f32_dpp v177, v97, v215 row_shl:15 row_mask:0xf bank_mask:0xf
	v_fmac_f32_dpp v178, v98, v216 row_shl:15 row_mask:0xf bank_mask:0xf
	v_fmac_f32_dpp v179, v99, v217 row_shl:15 row_mask:0xf bank_mask:0xf
	v_fmac_f32_dpp v172, v112, v194 row_shl:14 row_mask:0xf bank_mask:0xf
	v_fmac_f32_dpp v173, v113, v195 row_shl:14 row_mask:0xf bank_mask:0xf
	v_fmac_f32_dpp v174, v114, v196 row_shl:14 row_mask:0xf bank_mask:0xf
	v_fmac_f32_dpp v175, v115, v197 row_shl:14 row_mask:0xf bank_mask:0xf
	v_fmac_f32_dpp v176, v96, v210 row_shl:14 row_mask:0xf bank_mask:0xf
	v_fmac_f32_dpp v177, v97, v211 row_shl:14 row_mask:0xf bank_mask:0xf
	v_fmac_f32_dpp v178, v98, v212 row_shl:14 row_mask:0xf bank_mask:0xf
	v_fmac_f32_dpp v179, v99, v213 row_shl:14 row_mask:0xf bank_mask:0xf
	v_mul_f32_e32 v180, 0x3d372713, v172
	v_mul_f32_e32 v181, 0x3d372713, v173
	v_mul_f32_e32 v182, 0x3d372713, v174
	v_mul_f32_e32 v183, 0x3d372713, v175
	v_mul_f32_e32 v180, v172, v180
	v_mul_f32_e32 v181, v173, v181
	v_mul_f32_e32 v182, v174, v182
	v_mul_f32_e32 v183, v175, v183
	v_fma_f32 v180, v172, v180, v172
	v_fma_f32 v181, v173, v181, v173
	v_fma_f32 v182, v174, v182, v174
	v_fma_f32 v183, v175, v183, v175
	v_mul_f32_e32 v180, 0xc0135761, v180
	v_mul_f32_e32 v181, 0xc0135761, v181
	v_mul_f32_e32 v182, 0xc0135761, v182
	v_mul_f32_e32 v183, 0xc0135761, v183
	v_exp_f32_e32 v180, v180
	v_exp_f32_e32 v181, v181
	v_exp_f32_e32 v182, v182
	v_exp_f32_e32 v183, v183
	v_add_f32_e32 v180, 1.0, v180
	v_add_f32_e32 v181, 1.0, v181
	v_add_f32_e32 v182, 1.0, v182
	v_add_f32_e32 v183, 1.0, v183
	v_rcp_f32_e32 v180, v180
	v_rcp_f32_e32 v181, v181
	v_rcp_f32_e32 v182, v182
	v_rcp_f32_e32 v183, v183
	v_mul_f32_e32 v172, v172, v180
	v_mul_f32_e32 v173, v173, v181
	v_mul_f32_e32 v174, v174, v182
	v_mul_f32_e32 v175, v175, v183
	v_mul_f32_e32 v172, v172, v176
	v_mul_f32_e32 v173, v173, v177
	v_mul_f32_e32 v174, v174, v178
	v_mul_f32_e32 v175, v175, v179
	v_cvt_pk_bf16_f32 v100, v172, v173
	v_cvt_pk_bf16_f32 v101, v174, v175
	v_fma_f32 v172, v202, v112, v206
	v_fma_f32 v173, v203, v113, v207
	v_fma_f32 v174, v204, v114, v208
	v_fma_f32 v175, v205, v115, v209
	v_fma_f32 v176, v218, v96, v222
	v_fma_f32 v177, v219, v97, v223
	v_fma_f32 v178, v220, v98, v224
	v_fma_f32 v179, v221, v99, v225
	v_fmac_f32_dpp v172, v112, v198 row_shr:1 row_mask:0xf bank_mask:0xf
	v_fmac_f32_dpp v173, v113, v199 row_shr:1 row_mask:0xf bank_mask:0xf
	v_fmac_f32_dpp v174, v114, v200 row_shr:1 row_mask:0xf bank_mask:0xf
	v_fmac_f32_dpp v175, v115, v201 row_shr:1 row_mask:0xf bank_mask:0xf
	v_fmac_f32_dpp v176, v96, v214 row_shr:1 row_mask:0xf bank_mask:0xf
	v_fmac_f32_dpp v177, v97, v215 row_shr:1 row_mask:0xf bank_mask:0xf
	v_fmac_f32_dpp v178, v98, v216 row_shr:1 row_mask:0xf bank_mask:0xf
	v_fmac_f32_dpp v179, v99, v217 row_shr:1 row_mask:0xf bank_mask:0xf
	v_fmac_f32_dpp v172, v112, v194 row_shr:2 row_mask:0xf bank_mask:0xf
	v_fmac_f32_dpp v173, v113, v195 row_shr:2 row_mask:0xf bank_mask:0xf
	v_fmac_f32_dpp v174, v114, v196 row_shr:2 row_mask:0xf bank_mask:0xf
	v_fmac_f32_dpp v175, v115, v197 row_shr:2 row_mask:0xf bank_mask:0xf
	v_fmac_f32_dpp v176, v96, v210 row_shr:2 row_mask:0xf bank_mask:0xf
	v_fmac_f32_dpp v177, v97, v211 row_shr:2 row_mask:0xf bank_mask:0xf
	v_fmac_f32_dpp v178, v98, v212 row_shr:2 row_mask:0xf bank_mask:0xf
	v_fmac_f32_dpp v179, v99, v213 row_shr:2 row_mask:0xf bank_mask:0xf
	v_fmac_f32_dpp v172, v124, v198 row_shl:15 row_mask:0xf bank_mask:0xf
	v_fmac_f32_dpp v173, v125, v199 row_shl:15 row_mask:0xf bank_mask:0xf
	v_fmac_f32_dpp v174, v126, v200 row_shl:15 row_mask:0xf bank_mask:0xf
	v_fmac_f32_dpp v175, v127, v201 row_shl:15 row_mask:0xf bank_mask:0xf
	v_fmac_f32_dpp v176, v116, v214 row_shl:15 row_mask:0xf bank_mask:0xf
	v_fmac_f32_dpp v177, v117, v215 row_shl:15 row_mask:0xf bank_mask:0xf
	v_fmac_f32_dpp v178, v118, v216 row_shl:15 row_mask:0xf bank_mask:0xf
	v_fmac_f32_dpp v179, v119, v217 row_shl:15 row_mask:0xf bank_mask:0xf
	v_fmac_f32_dpp v172, v124, v194 row_shl:14 row_mask:0xf bank_mask:0xf
	v_fmac_f32_dpp v173, v125, v195 row_shl:14 row_mask:0xf bank_mask:0xf
	v_fmac_f32_dpp v174, v126, v196 row_shl:14 row_mask:0xf bank_mask:0xf
	v_fmac_f32_dpp v175, v127, v197 row_shl:14 row_mask:0xf bank_mask:0xf
	v_fmac_f32_dpp v176, v116, v210 row_shl:14 row_mask:0xf bank_mask:0xf
	v_fmac_f32_dpp v177, v117, v211 row_shl:14 row_mask:0xf bank_mask:0xf
	v_fmac_f32_dpp v178, v118, v212 row_shl:14 row_mask:0xf bank_mask:0xf
	v_fmac_f32_dpp v179, v119, v213 row_shl:14 row_mask:0xf bank_mask:0xf
	v_mul_f32_e32 v180, 0x3d372713, v172
	v_mul_f32_e32 v181, 0x3d372713, v173
	v_mul_f32_e32 v182, 0x3d372713, v174
	v_mul_f32_e32 v183, 0x3d372713, v175
	v_mul_f32_e32 v180, v172, v180
	v_mul_f32_e32 v181, v173, v181
	v_mul_f32_e32 v182, v174, v182
	v_mul_f32_e32 v183, v175, v183
	v_fma_f32 v180, v172, v180, v172
	v_fma_f32 v181, v173, v181, v173
	v_fma_f32 v182, v174, v182, v174
	v_fma_f32 v183, v175, v183, v175
	v_mul_f32_e32 v180, 0xc0135761, v180
	v_mul_f32_e32 v181, 0xc0135761, v181
	v_mul_f32_e32 v182, 0xc0135761, v182
	v_mul_f32_e32 v183, 0xc0135761, v183
	v_exp_f32_e32 v180, v180
	v_exp_f32_e32 v181, v181
	v_exp_f32_e32 v182, v182
	v_exp_f32_e32 v183, v183
	v_add_f32_e32 v180, 1.0, v180
	v_add_f32_e32 v181, 1.0, v181
	v_add_f32_e32 v182, 1.0, v182
	v_add_f32_e32 v183, 1.0, v183
	v_rcp_f32_e32 v180, v180
	v_rcp_f32_e32 v181, v181
	v_rcp_f32_e32 v182, v182
	v_rcp_f32_e32 v183, v183
	v_mul_f32_e32 v172, v172, v180
	v_mul_f32_e32 v173, v173, v181
	v_mul_f32_e32 v174, v174, v182
	v_mul_f32_e32 v175, v175, v183
	v_mul_f32_e32 v172, v172, v176
	v_mul_f32_e32 v173, v173, v177
	v_mul_f32_e32 v174, v174, v178
	v_mul_f32_e32 v175, v175, v179
	v_cvt_pk_bf16_f32 v112, v172, v173
	v_cvt_pk_bf16_f32 v113, v174, v175
	v_fma_f32 v172, v202, v124, v206
	v_fma_f32 v173, v203, v125, v207
	v_fma_f32 v174, v204, v126, v208
	v_fma_f32 v175, v205, v127, v209
	v_fma_f32 v176, v218, v116, v222
	v_fma_f32 v177, v219, v117, v223
	v_fma_f32 v178, v220, v118, v224
	v_fma_f32 v179, v221, v119, v225
	v_fmac_f32_dpp v172, v124, v198 row_shr:1 row_mask:0xf bank_mask:0xf
	v_fmac_f32_dpp v173, v125, v199 row_shr:1 row_mask:0xf bank_mask:0xf
	v_fmac_f32_dpp v174, v126, v200 row_shr:1 row_mask:0xf bank_mask:0xf
	v_fmac_f32_dpp v175, v127, v201 row_shr:1 row_mask:0xf bank_mask:0xf
	v_fmac_f32_dpp v176, v116, v214 row_shr:1 row_mask:0xf bank_mask:0xf
	v_fmac_f32_dpp v177, v117, v215 row_shr:1 row_mask:0xf bank_mask:0xf
	v_fmac_f32_dpp v178, v118, v216 row_shr:1 row_mask:0xf bank_mask:0xf
	v_fmac_f32_dpp v179, v119, v217 row_shr:1 row_mask:0xf bank_mask:0xf
	v_fmac_f32_dpp v172, v124, v194 row_shr:2 row_mask:0xf bank_mask:0xf
	v_fmac_f32_dpp v173, v125, v195 row_shr:2 row_mask:0xf bank_mask:0xf
	v_fmac_f32_dpp v174, v126, v196 row_shr:2 row_mask:0xf bank_mask:0xf
	v_fmac_f32_dpp v175, v127, v197 row_shr:2 row_mask:0xf bank_mask:0xf
	v_fmac_f32_dpp v176, v116, v210 row_shr:2 row_mask:0xf bank_mask:0xf
	v_fmac_f32_dpp v177, v117, v211 row_shr:2 row_mask:0xf bank_mask:0xf
	v_fmac_f32_dpp v178, v118, v212 row_shr:2 row_mask:0xf bank_mask:0xf
	v_fmac_f32_dpp v179, v119, v213 row_shr:2 row_mask:0xf bank_mask:0xf
	v_fmac_f32_dpp v172, v128, v198 row_shl:15 row_mask:0xf bank_mask:0xf
	v_fmac_f32_dpp v173, v129, v199 row_shl:15 row_mask:0xf bank_mask:0xf
	v_fmac_f32_dpp v174, v130, v200 row_shl:15 row_mask:0xf bank_mask:0xf
	v_fmac_f32_dpp v175, v131, v201 row_shl:15 row_mask:0xf bank_mask:0xf
	v_fmac_f32_dpp v176, v132, v214 row_shl:15 row_mask:0xf bank_mask:0xf
	v_fmac_f32_dpp v177, v133, v215 row_shl:15 row_mask:0xf bank_mask:0xf
	v_fmac_f32_dpp v178, v134, v216 row_shl:15 row_mask:0xf bank_mask:0xf
	v_fmac_f32_dpp v179, v135, v217 row_shl:15 row_mask:0xf bank_mask:0xf
	v_fmac_f32_dpp v172, v128, v194 row_shl:14 row_mask:0xf bank_mask:0xf
	v_fmac_f32_dpp v173, v129, v195 row_shl:14 row_mask:0xf bank_mask:0xf
	v_fmac_f32_dpp v174, v130, v196 row_shl:14 row_mask:0xf bank_mask:0xf
	v_fmac_f32_dpp v175, v131, v197 row_shl:14 row_mask:0xf bank_mask:0xf
	v_fmac_f32_dpp v176, v132, v210 row_shl:14 row_mask:0xf bank_mask:0xf
	v_fmac_f32_dpp v177, v133, v211 row_shl:14 row_mask:0xf bank_mask:0xf
	v_fmac_f32_dpp v178, v134, v212 row_shl:14 row_mask:0xf bank_mask:0xf
	v_fmac_f32_dpp v179, v135, v213 row_shl:14 row_mask:0xf bank_mask:0xf
	v_mul_f32_e32 v180, 0x3d372713, v172
	v_mul_f32_e32 v181, 0x3d372713, v173
	v_mul_f32_e32 v182, 0x3d372713, v174
	v_mul_f32_e32 v183, 0x3d372713, v175
	v_mul_f32_e32 v180, v172, v180
	v_mul_f32_e32 v181, v173, v181
	v_mul_f32_e32 v182, v174, v182
	v_mul_f32_e32 v183, v175, v183
	v_fma_f32 v180, v172, v180, v172
	v_fma_f32 v181, v173, v181, v173
	v_fma_f32 v182, v174, v182, v174
	v_fma_f32 v183, v175, v183, v175
	v_mul_f32_e32 v180, 0xc0135761, v180
	v_mul_f32_e32 v181, 0xc0135761, v181
	v_mul_f32_e32 v182, 0xc0135761, v182
	v_mul_f32_e32 v183, 0xc0135761, v183
	v_exp_f32_e32 v180, v180
	v_exp_f32_e32 v181, v181
	v_exp_f32_e32 v182, v182
	v_exp_f32_e32 v183, v183
	v_add_f32_e32 v180, 1.0, v180
	v_add_f32_e32 v181, 1.0, v181
	v_add_f32_e32 v182, 1.0, v182
	v_add_f32_e32 v183, 1.0, v183
	v_rcp_f32_e32 v180, v180
	v_rcp_f32_e32 v181, v181
	v_rcp_f32_e32 v182, v182
	v_rcp_f32_e32 v183, v183
	v_mul_f32_e32 v172, v172, v180
	v_mul_f32_e32 v173, v173, v181
	v_mul_f32_e32 v174, v174, v182
	v_mul_f32_e32 v175, v175, v183
	v_mul_f32_e32 v172, v172, v176
	v_mul_f32_e32 v173, v173, v177
	v_mul_f32_e32 v174, v174, v178
	v_mul_f32_e32 v175, v175, v179
	v_cvt_pk_bf16_f32 v124, v172, v173
	v_cvt_pk_bf16_f32 v125, v174, v175
	v_fma_f32 v172, v202, v20, v206
	v_fma_f32 v173, v203, v21, v207
	v_fma_f32 v174, v204, v22, v208
	v_fma_f32 v175, v205, v23, v209
	v_fma_f32 v176, v218, v4, v222
	v_fma_f32 v177, v219, v5, v223
	v_fma_f32 v178, v220, v6, v224
	v_fma_f32 v179, v221, v7, v225
	v_fmac_f32_dpp v172, v20, v198 row_shr:1 row_mask:0xf bank_mask:0xf
	v_fmac_f32_dpp v173, v21, v199 row_shr:1 row_mask:0xf bank_mask:0xf
	v_fmac_f32_dpp v174, v22, v200 row_shr:1 row_mask:0xf bank_mask:0xf
	v_fmac_f32_dpp v175, v23, v201 row_shr:1 row_mask:0xf bank_mask:0xf
	v_fmac_f32_dpp v176, v4, v214 row_shr:1 row_mask:0xf bank_mask:0xf
	v_fmac_f32_dpp v177, v5, v215 row_shr:1 row_mask:0xf bank_mask:0xf
	v_fmac_f32_dpp v178, v6, v216 row_shr:1 row_mask:0xf bank_mask:0xf
	v_fmac_f32_dpp v179, v7, v217 row_shr:1 row_mask:0xf bank_mask:0xf
	v_fmac_f32_dpp v172, v20, v194 row_shr:2 row_mask:0xf bank_mask:0xf
	v_fmac_f32_dpp v173, v21, v195 row_shr:2 row_mask:0xf bank_mask:0xf
	v_fmac_f32_dpp v174, v22, v196 row_shr:2 row_mask:0xf bank_mask:0xf
	v_fmac_f32_dpp v175, v23, v197 row_shr:2 row_mask:0xf bank_mask:0xf
	v_fmac_f32_dpp v176, v4, v210 row_shr:2 row_mask:0xf bank_mask:0xf
	v_fmac_f32_dpp v177, v5, v211 row_shr:2 row_mask:0xf bank_mask:0xf
	v_fmac_f32_dpp v178, v6, v212 row_shr:2 row_mask:0xf bank_mask:0xf
	v_fmac_f32_dpp v179, v7, v213 row_shr:2 row_mask:0xf bank_mask:0xf
	v_fmac_f32_dpp v172, v36, v198 row_shl:15 row_mask:0xf bank_mask:0xf
	v_fmac_f32_dpp v173, v37, v199 row_shl:15 row_mask:0xf bank_mask:0xf
	v_fmac_f32_dpp v174, v38, v200 row_shl:15 row_mask:0xf bank_mask:0xf
	v_fmac_f32_dpp v175, v39, v201 row_shl:15 row_mask:0xf bank_mask:0xf
	v_fmac_f32_dpp v176, v16, v214 row_shl:15 row_mask:0xf bank_mask:0xf
	v_fmac_f32_dpp v177, v17, v215 row_shl:15 row_mask:0xf bank_mask:0xf
	v_fmac_f32_dpp v178, v18, v216 row_shl:15 row_mask:0xf bank_mask:0xf
	v_fmac_f32_dpp v179, v19, v217 row_shl:15 row_mask:0xf bank_mask:0xf
	v_fmac_f32_dpp v172, v36, v194 row_shl:14 row_mask:0xf bank_mask:0xf
	v_fmac_f32_dpp v173, v37, v195 row_shl:14 row_mask:0xf bank_mask:0xf
	v_fmac_f32_dpp v174, v38, v196 row_shl:14 row_mask:0xf bank_mask:0xf
	v_fmac_f32_dpp v175, v39, v197 row_shl:14 row_mask:0xf bank_mask:0xf
	v_fmac_f32_dpp v176, v16, v210 row_shl:14 row_mask:0xf bank_mask:0xf
	v_fmac_f32_dpp v177, v17, v211 row_shl:14 row_mask:0xf bank_mask:0xf
	v_fmac_f32_dpp v178, v18, v212 row_shl:14 row_mask:0xf bank_mask:0xf
	v_fmac_f32_dpp v179, v19, v213 row_shl:14 row_mask:0xf bank_mask:0xf
	v_mul_f32_e32 v180, 0x3d372713, v172
	v_mul_f32_e32 v181, 0x3d372713, v173
	v_mul_f32_e32 v182, 0x3d372713, v174
	v_mul_f32_e32 v183, 0x3d372713, v175
	v_mul_f32_e32 v180, v172, v180
	v_mul_f32_e32 v181, v173, v181
	v_mul_f32_e32 v182, v174, v182
	v_mul_f32_e32 v183, v175, v183
	v_fma_f32 v180, v172, v180, v172
	v_fma_f32 v181, v173, v181, v173
	v_fma_f32 v182, v174, v182, v174
	v_fma_f32 v183, v175, v183, v175
	v_mul_f32_e32 v180, 0xc0135761, v180
	v_mul_f32_e32 v181, 0xc0135761, v181
	v_mul_f32_e32 v182, 0xc0135761, v182
	v_mul_f32_e32 v183, 0xc0135761, v183
	v_exp_f32_e32 v180, v180
	v_exp_f32_e32 v181, v181
	v_exp_f32_e32 v182, v182
	v_exp_f32_e32 v183, v183
	v_add_f32_e32 v180, 1.0, v180
	v_add_f32_e32 v181, 1.0, v181
	v_add_f32_e32 v182, 1.0, v182
	v_add_f32_e32 v183, 1.0, v183
	v_rcp_f32_e32 v180, v180
	v_rcp_f32_e32 v181, v181
	v_rcp_f32_e32 v182, v182
	v_rcp_f32_e32 v183, v183
	v_mul_f32_e32 v172, v172, v180
	v_mul_f32_e32 v173, v173, v181
	v_mul_f32_e32 v174, v174, v182
	v_mul_f32_e32 v175, v175, v183
	v_mul_f32_e32 v172, v172, v176
	v_mul_f32_e32 v173, v173, v177
	v_mul_f32_e32 v174, v174, v178
	v_mul_f32_e32 v175, v175, v179
	v_cvt_pk_bf16_f32 v20, v172, v173
	v_cvt_pk_bf16_f32 v21, v174, v175
	v_fma_f32 v172, v202, v36, v206
	v_fma_f32 v173, v203, v37, v207
	v_fma_f32 v174, v204, v38, v208
	v_fma_f32 v175, v205, v39, v209
	v_fma_f32 v176, v218, v16, v222
	v_fma_f32 v177, v219, v17, v223
	v_fma_f32 v178, v220, v18, v224
	v_fma_f32 v179, v221, v19, v225
	v_fmac_f32_dpp v172, v36, v198 row_shr:1 row_mask:0xf bank_mask:0xf
	v_fmac_f32_dpp v173, v37, v199 row_shr:1 row_mask:0xf bank_mask:0xf
	v_fmac_f32_dpp v174, v38, v200 row_shr:1 row_mask:0xf bank_mask:0xf
	v_fmac_f32_dpp v175, v39, v201 row_shr:1 row_mask:0xf bank_mask:0xf
	v_fmac_f32_dpp v176, v16, v214 row_shr:1 row_mask:0xf bank_mask:0xf
	v_fmac_f32_dpp v177, v17, v215 row_shr:1 row_mask:0xf bank_mask:0xf
	v_fmac_f32_dpp v178, v18, v216 row_shr:1 row_mask:0xf bank_mask:0xf
	v_fmac_f32_dpp v179, v19, v217 row_shr:1 row_mask:0xf bank_mask:0xf
	v_fmac_f32_dpp v172, v36, v194 row_shr:2 row_mask:0xf bank_mask:0xf
	v_fmac_f32_dpp v173, v37, v195 row_shr:2 row_mask:0xf bank_mask:0xf
	v_fmac_f32_dpp v174, v38, v196 row_shr:2 row_mask:0xf bank_mask:0xf
	v_fmac_f32_dpp v175, v39, v197 row_shr:2 row_mask:0xf bank_mask:0xf
	v_fmac_f32_dpp v176, v16, v210 row_shr:2 row_mask:0xf bank_mask:0xf
	v_fmac_f32_dpp v177, v17, v211 row_shr:2 row_mask:0xf bank_mask:0xf
	v_fmac_f32_dpp v178, v18, v212 row_shr:2 row_mask:0xf bank_mask:0xf
	v_fmac_f32_dpp v179, v19, v213 row_shr:2 row_mask:0xf bank_mask:0xf
	v_fmac_f32_dpp v172, v52, v198 row_shl:15 row_mask:0xf bank_mask:0xf
	v_fmac_f32_dpp v173, v53, v199 row_shl:15 row_mask:0xf bank_mask:0xf
	v_fmac_f32_dpp v174, v54, v200 row_shl:15 row_mask:0xf bank_mask:0xf
	v_fmac_f32_dpp v175, v55, v201 row_shl:15 row_mask:0xf bank_mask:0xf
	v_fmac_f32_dpp v176, v32, v214 row_shl:15 row_mask:0xf bank_mask:0xf
	v_fmac_f32_dpp v177, v33, v215 row_shl:15 row_mask:0xf bank_mask:0xf
	v_fmac_f32_dpp v178, v34, v216 row_shl:15 row_mask:0xf bank_mask:0xf
	v_fmac_f32_dpp v179, v35, v217 row_shl:15 row_mask:0xf bank_mask:0xf
	v_fmac_f32_dpp v172, v52, v194 row_shl:14 row_mask:0xf bank_mask:0xf
	v_fmac_f32_dpp v173, v53, v195 row_shl:14 row_mask:0xf bank_mask:0xf
	v_fmac_f32_dpp v174, v54, v196 row_shl:14 row_mask:0xf bank_mask:0xf
	v_fmac_f32_dpp v175, v55, v197 row_shl:14 row_mask:0xf bank_mask:0xf
	v_fmac_f32_dpp v176, v32, v210 row_shl:14 row_mask:0xf bank_mask:0xf
	v_fmac_f32_dpp v177, v33, v211 row_shl:14 row_mask:0xf bank_mask:0xf
	v_fmac_f32_dpp v178, v34, v212 row_shl:14 row_mask:0xf bank_mask:0xf
	v_fmac_f32_dpp v179, v35, v213 row_shl:14 row_mask:0xf bank_mask:0xf
	v_mul_f32_e32 v180, 0x3d372713, v172
	v_mul_f32_e32 v181, 0x3d372713, v173
	v_mul_f32_e32 v182, 0x3d372713, v174
	v_mul_f32_e32 v183, 0x3d372713, v175
	v_mul_f32_e32 v180, v172, v180
	v_mul_f32_e32 v181, v173, v181
	v_mul_f32_e32 v182, v174, v182
	v_mul_f32_e32 v183, v175, v183
	v_fma_f32 v180, v172, v180, v172
	v_fma_f32 v181, v173, v181, v173
	v_fma_f32 v182, v174, v182, v174
	v_fma_f32 v183, v175, v183, v175
	v_mul_f32_e32 v180, 0xc0135761, v180
	v_mul_f32_e32 v181, 0xc0135761, v181
	v_mul_f32_e32 v182, 0xc0135761, v182
	v_mul_f32_e32 v183, 0xc0135761, v183
	v_exp_f32_e32 v180, v180
	v_exp_f32_e32 v181, v181
	v_exp_f32_e32 v182, v182
	v_exp_f32_e32 v183, v183
	v_add_f32_e32 v180, 1.0, v180
	v_add_f32_e32 v181, 1.0, v181
	v_add_f32_e32 v182, 1.0, v182
	v_add_f32_e32 v183, 1.0, v183
	v_rcp_f32_e32 v180, v180
	v_rcp_f32_e32 v181, v181
	v_rcp_f32_e32 v182, v182
	v_rcp_f32_e32 v183, v183
	v_mul_f32_e32 v172, v172, v180
	v_mul_f32_e32 v173, v173, v181
	v_mul_f32_e32 v174, v174, v182
	v_mul_f32_e32 v175, v175, v183
	v_mul_f32_e32 v172, v172, v176
	v_mul_f32_e32 v173, v173, v177
	v_mul_f32_e32 v174, v174, v178
	v_mul_f32_e32 v175, v175, v179
	v_cvt_pk_bf16_f32 v36, v172, v173
	v_cvt_pk_bf16_f32 v37, v174, v175
	v_fma_f32 v172, v202, v52, v206
	v_fma_f32 v173, v203, v53, v207
	v_fma_f32 v174, v204, v54, v208
	v_fma_f32 v175, v205, v55, v209
	v_fma_f32 v176, v218, v32, v222
	v_fma_f32 v177, v219, v33, v223
	v_fma_f32 v178, v220, v34, v224
	v_fma_f32 v179, v221, v35, v225
	v_fmac_f32_dpp v172, v52, v198 row_shr:1 row_mask:0xf bank_mask:0xf
	v_fmac_f32_dpp v173, v53, v199 row_shr:1 row_mask:0xf bank_mask:0xf
	v_fmac_f32_dpp v174, v54, v200 row_shr:1 row_mask:0xf bank_mask:0xf
	v_fmac_f32_dpp v175, v55, v201 row_shr:1 row_mask:0xf bank_mask:0xf
	v_fmac_f32_dpp v176, v32, v214 row_shr:1 row_mask:0xf bank_mask:0xf
	v_fmac_f32_dpp v177, v33, v215 row_shr:1 row_mask:0xf bank_mask:0xf
	v_fmac_f32_dpp v178, v34, v216 row_shr:1 row_mask:0xf bank_mask:0xf
	v_fmac_f32_dpp v179, v35, v217 row_shr:1 row_mask:0xf bank_mask:0xf
	v_fmac_f32_dpp v172, v52, v194 row_shr:2 row_mask:0xf bank_mask:0xf
	v_fmac_f32_dpp v173, v53, v195 row_shr:2 row_mask:0xf bank_mask:0xf
	v_fmac_f32_dpp v174, v54, v196 row_shr:2 row_mask:0xf bank_mask:0xf
	v_fmac_f32_dpp v175, v55, v197 row_shr:2 row_mask:0xf bank_mask:0xf
	v_fmac_f32_dpp v176, v32, v210 row_shr:2 row_mask:0xf bank_mask:0xf
	v_fmac_f32_dpp v177, v33, v211 row_shr:2 row_mask:0xf bank_mask:0xf
	v_fmac_f32_dpp v178, v34, v212 row_shr:2 row_mask:0xf bank_mask:0xf
	v_fmac_f32_dpp v179, v35, v213 row_shr:2 row_mask:0xf bank_mask:0xf
	v_fmac_f32_dpp v172, v60, v198 row_shl:15 row_mask:0xf bank_mask:0xf
	v_fmac_f32_dpp v173, v61, v199 row_shl:15 row_mask:0xf bank_mask:0xf
	v_fmac_f32_dpp v174, v62, v200 row_shl:15 row_mask:0xf bank_mask:0xf
	v_fmac_f32_dpp v175, v63, v201 row_shl:15 row_mask:0xf bank_mask:0xf
	v_fmac_f32_dpp v176, v48, v214 row_shl:15 row_mask:0xf bank_mask:0xf
	v_fmac_f32_dpp v177, v49, v215 row_shl:15 row_mask:0xf bank_mask:0xf
	v_fmac_f32_dpp v178, v50, v216 row_shl:15 row_mask:0xf bank_mask:0xf
	v_fmac_f32_dpp v179, v51, v217 row_shl:15 row_mask:0xf bank_mask:0xf
	v_fmac_f32_dpp v172, v60, v194 row_shl:14 row_mask:0xf bank_mask:0xf
	v_fmac_f32_dpp v173, v61, v195 row_shl:14 row_mask:0xf bank_mask:0xf
	v_fmac_f32_dpp v174, v62, v196 row_shl:14 row_mask:0xf bank_mask:0xf
	v_fmac_f32_dpp v175, v63, v197 row_shl:14 row_mask:0xf bank_mask:0xf
	v_fmac_f32_dpp v176, v48, v210 row_shl:14 row_mask:0xf bank_mask:0xf
	v_fmac_f32_dpp v177, v49, v211 row_shl:14 row_mask:0xf bank_mask:0xf
	v_fmac_f32_dpp v178, v50, v212 row_shl:14 row_mask:0xf bank_mask:0xf
	v_fmac_f32_dpp v179, v51, v213 row_shl:14 row_mask:0xf bank_mask:0xf
	v_mul_f32_e32 v180, 0x3d372713, v172
	v_mul_f32_e32 v181, 0x3d372713, v173
	v_mul_f32_e32 v182, 0x3d372713, v174
	v_mul_f32_e32 v183, 0x3d372713, v175
	v_mul_f32_e32 v180, v172, v180
	v_mul_f32_e32 v181, v173, v181
	v_mul_f32_e32 v182, v174, v182
	v_mul_f32_e32 v183, v175, v183
	v_fma_f32 v180, v172, v180, v172
	v_fma_f32 v181, v173, v181, v173
	v_fma_f32 v182, v174, v182, v174
	v_fma_f32 v183, v175, v183, v175
	v_mul_f32_e32 v180, 0xc0135761, v180
	v_mul_f32_e32 v181, 0xc0135761, v181
	v_mul_f32_e32 v182, 0xc0135761, v182
	v_mul_f32_e32 v183, 0xc0135761, v183
	v_exp_f32_e32 v180, v180
	v_exp_f32_e32 v181, v181
	v_exp_f32_e32 v182, v182
	v_exp_f32_e32 v183, v183
	v_add_f32_e32 v180, 1.0, v180
	v_add_f32_e32 v181, 1.0, v181
	v_add_f32_e32 v182, 1.0, v182
	v_add_f32_e32 v183, 1.0, v183
	v_rcp_f32_e32 v180, v180
	v_rcp_f32_e32 v181, v181
	v_rcp_f32_e32 v182, v182
	v_rcp_f32_e32 v183, v183
	v_mul_f32_e32 v172, v172, v180
	v_mul_f32_e32 v173, v173, v181
	v_mul_f32_e32 v174, v174, v182
	v_mul_f32_e32 v175, v175, v183
	v_mul_f32_e32 v172, v172, v176
	v_mul_f32_e32 v173, v173, v177
	v_mul_f32_e32 v174, v174, v178
	v_mul_f32_e32 v175, v175, v179
	v_cvt_pk_bf16_f32 v52, v172, v173
	v_cvt_pk_bf16_f32 v53, v174, v175
	v_fma_f32 v172, v202, v60, v206
	v_fma_f32 v173, v203, v61, v207
	v_fma_f32 v174, v204, v62, v208
	v_fma_f32 v175, v205, v63, v209
	v_fma_f32 v176, v218, v48, v222
	v_fma_f32 v177, v219, v49, v223
	v_fma_f32 v178, v220, v50, v224
	v_fma_f32 v179, v221, v51, v225
	v_fmac_f32_dpp v172, v60, v198 row_shr:1 row_mask:0xf bank_mask:0xf
	v_fmac_f32_dpp v173, v61, v199 row_shr:1 row_mask:0xf bank_mask:0xf
	v_fmac_f32_dpp v174, v62, v200 row_shr:1 row_mask:0xf bank_mask:0xf
	v_fmac_f32_dpp v175, v63, v201 row_shr:1 row_mask:0xf bank_mask:0xf
	v_fmac_f32_dpp v176, v48, v214 row_shr:1 row_mask:0xf bank_mask:0xf
	v_fmac_f32_dpp v177, v49, v215 row_shr:1 row_mask:0xf bank_mask:0xf
	v_fmac_f32_dpp v178, v50, v216 row_shr:1 row_mask:0xf bank_mask:0xf
	v_fmac_f32_dpp v179, v51, v217 row_shr:1 row_mask:0xf bank_mask:0xf
	v_fmac_f32_dpp v172, v60, v194 row_shr:2 row_mask:0xf bank_mask:0xf
	v_fmac_f32_dpp v173, v61, v195 row_shr:2 row_mask:0xf bank_mask:0xf
	v_fmac_f32_dpp v174, v62, v196 row_shr:2 row_mask:0xf bank_mask:0xf
	v_fmac_f32_dpp v175, v63, v197 row_shr:2 row_mask:0xf bank_mask:0xf
	v_fmac_f32_dpp v176, v48, v210 row_shr:2 row_mask:0xf bank_mask:0xf
	v_fmac_f32_dpp v177, v49, v211 row_shr:2 row_mask:0xf bank_mask:0xf
	v_fmac_f32_dpp v178, v50, v212 row_shr:2 row_mask:0xf bank_mask:0xf
	v_fmac_f32_dpp v179, v51, v213 row_shr:2 row_mask:0xf bank_mask:0xf
	v_fmac_f32_dpp v172, v136, v198 row_shl:15 row_mask:0xf bank_mask:0xf
	v_fmac_f32_dpp v173, v137, v199 row_shl:15 row_mask:0xf bank_mask:0xf
	v_fmac_f32_dpp v174, v138, v200 row_shl:15 row_mask:0xf bank_mask:0xf
	v_fmac_f32_dpp v175, v139, v201 row_shl:15 row_mask:0xf bank_mask:0xf
	v_fmac_f32_dpp v176, v140, v214 row_shl:15 row_mask:0xf bank_mask:0xf
	v_fmac_f32_dpp v177, v141, v215 row_shl:15 row_mask:0xf bank_mask:0xf
	v_fmac_f32_dpp v178, v142, v216 row_shl:15 row_mask:0xf bank_mask:0xf
	v_fmac_f32_dpp v179, v143, v217 row_shl:15 row_mask:0xf bank_mask:0xf
	v_fmac_f32_dpp v172, v136, v194 row_shl:14 row_mask:0xf bank_mask:0xf
	v_fmac_f32_dpp v173, v137, v195 row_shl:14 row_mask:0xf bank_mask:0xf
	v_fmac_f32_dpp v174, v138, v196 row_shl:14 row_mask:0xf bank_mask:0xf
	v_fmac_f32_dpp v175, v139, v197 row_shl:14 row_mask:0xf bank_mask:0xf
	v_fmac_f32_dpp v176, v140, v210 row_shl:14 row_mask:0xf bank_mask:0xf
	v_fmac_f32_dpp v177, v141, v211 row_shl:14 row_mask:0xf bank_mask:0xf
	v_fmac_f32_dpp v178, v142, v212 row_shl:14 row_mask:0xf bank_mask:0xf
	v_fmac_f32_dpp v179, v143, v213 row_shl:14 row_mask:0xf bank_mask:0xf
	v_mul_f32_e32 v180, 0x3d372713, v172
	v_mul_f32_e32 v181, 0x3d372713, v173
	v_mul_f32_e32 v182, 0x3d372713, v174
	v_mul_f32_e32 v183, 0x3d372713, v175
	v_mul_f32_e32 v180, v172, v180
	v_mul_f32_e32 v181, v173, v181
	v_mul_f32_e32 v182, v174, v182
	v_mul_f32_e32 v183, v175, v183
	v_fma_f32 v180, v172, v180, v172
	v_fma_f32 v181, v173, v181, v173
	v_fma_f32 v182, v174, v182, v174
	v_fma_f32 v183, v175, v183, v175
	v_mul_f32_e32 v180, 0xc0135761, v180
	v_mul_f32_e32 v181, 0xc0135761, v181
	v_mul_f32_e32 v182, 0xc0135761, v182
	v_mul_f32_e32 v183, 0xc0135761, v183
	v_exp_f32_e32 v180, v180
	v_exp_f32_e32 v181, v181
	v_exp_f32_e32 v182, v182
	v_exp_f32_e32 v183, v183
	v_add_f32_e32 v180, 1.0, v180
	v_add_f32_e32 v181, 1.0, v181
	v_add_f32_e32 v182, 1.0, v182
	v_add_f32_e32 v183, 1.0, v183
	v_rcp_f32_e32 v180, v180
	v_rcp_f32_e32 v181, v181
	v_rcp_f32_e32 v182, v182
	v_rcp_f32_e32 v183, v183
	v_mul_f32_e32 v172, v172, v180
	v_mul_f32_e32 v173, v173, v181
	v_mul_f32_e32 v174, v174, v182
	v_mul_f32_e32 v175, v175, v183
	v_mul_f32_e32 v172, v172, v176
	v_mul_f32_e32 v173, v173, v177
	v_mul_f32_e32 v174, v174, v178
	v_mul_f32_e32 v175, v175, v179
	v_cvt_pk_bf16_f32 v60, v172, v173
	v_cvt_pk_bf16_f32 v61, v174, v175
	global_load_dwordx4 v[226:229], v243, s[16:17] offset:16
	v_add_u32_e32 v242, 0x2c00, v243
	global_load_dwordx4 v[230:233], v242, s[16:17] offset:16
	global_load_dwordx4 v[206:209], v243, s[4:5] offset:16
	global_load_dwordx4 v[222:225], v243, s[30:31] offset:16
	global_load_dwordx4 v[194:197], v243, s[18:19] offset:16
	global_load_dwordx4 v[198:201], v243, s[34:35] offset:16
	global_load_dwordx4 v[202:205], v243, s[36:37] offset:16
	global_load_dwordx4 v[210:213], v243, s[38:39] offset:16
	global_load_dwordx4 v[214:217], v243, s[40:41] offset:16
	global_load_dwordx4 v[218:221], v243, s[42:43] offset:16
	ds_read_b128 v[128:131], v238 offset:16
	ds_read_b128 v[132:135], v238 offset:48
	ds_read_b128 v[136:139], v239 offset:16
	ds_read_b128 v[140:143], v239 offset:48
	s_waitcnt vmcnt(0)
	s_cmp_lg_u32 s33, 0
	s_cbranch_scc1 .Lepi9_wr1_2
	s_mov_b64 exec, s[52:53]
	v_add_f32_e32 v184, v120, v226
	v_add_f32_e32 v185, v121, v227
	v_add_f32_e32 v186, v122, v228
	v_add_f32_e32 v187, v123, v229
	v_cvt_pk_bf16_f32 v184, v184, v185
	v_cvt_pk_bf16_f32 v185, v186, v187
	global_store_dwordx2 v236, v[184:185], s[58:59] offset:8
	v_add_f32_e32 v188, v104, v230
	v_add_f32_e32 v189, v105, v231
	v_add_f32_e32 v190, v106, v232
	v_add_f32_e32 v191, v107, v233
	v_cvt_pk_bf16_f32 v188, v188, v189
	v_cvt_pk_bf16_f32 v189, v190, v191
	v_add_u32_e32 v241, 0x1600, v236
	global_store_dwordx2 v241, v[188:189], s[58:59] offset:8
	s_mov_b64 exec, -1
	s_branch .Lepi9_wrend_2
.Lepi9_wr1_2:
	s_mov_b64 exec, s[54:55]
	v_add_u32_e32 v242, 0xfffdf000, v236
	v_add_f32_e32 v184, v12, v226
	v_add_f32_e32 v185, v13, v227
	v_add_f32_e32 v186, v14, v228
	v_add_f32_e32 v187, v15, v229
	v_cvt_pk_bf16_f32 v184, v184, v185
	v_cvt_pk_bf16_f32 v185, v186, v187
	global_store_dwordx2 v242, v[184:185], s[58:59] offset:8
	v_add_f32_e32 v188, v0, v230
	v_add_f32_e32 v189, v1, v231
	v_add_f32_e32 v190, v2, v232
	v_add_f32_e32 v191, v3, v233
	v_cvt_pk_bf16_f32 v188, v188, v189
	v_cvt_pk_bf16_f32 v189, v190, v191
	v_add_u32_e32 v241, 0x1600, v242
	global_store_dwordx2 v241, v[188:189], s[58:59] offset:8
	s_mov_b64 exec, -1
.Lepi9_wrend_2:
	v_add_f32_e32 v180, v194, v198
	v_add_f32_e32 v181, v195, v199
	v_add_f32_e32 v182, v196, v200
	v_add_f32_e32 v183, v197, v201
	v_add_f32_e32 v180, v180, v202
	v_add_f32_e32 v181, v181, v203
	v_add_f32_e32 v182, v182, v204
	v_add_f32_e32 v183, v183, v205
	v_fma_f32 v206, v226, v180, v206
	v_fma_f32 v207, v227, v181, v207
	v_fma_f32 v208, v228, v182, v208
	v_fma_f32 v209, v229, v183, v209
	v_add_f32_e32 v180, v210, v214
	v_add_f32_e32 v181, v211, v215
	v_add_f32_e32 v182, v212, v216
	v_add_f32_e32 v183, v213, v217
	v_add_f32_e32 v180, v180, v218
	v_add_f32_e32 v181, v181, v219
	v_add_f32_e32 v182, v182, v220
	v_add_f32_e32 v183, v183, v221
	v_fma_f32 v222, v230, v180, v222
	v_fma_f32 v223, v231, v181, v223
	v_fma_f32 v224, v232, v182, v224
	v_fma_f32 v225, v233, v183, v225
	s_waitcnt lgkmcnt(0)
	v_fma_f32 v172, v202, v76, v206
	v_fma_f32 v173, v203, v77, v207
	v_fma_f32 v174, v204, v78, v208
	v_fma_f32 v175, v205, v79, v209
	v_fma_f32 v176, v218, v64, v222
	v_fma_f32 v177, v219, v65, v223
	v_fma_f32 v178, v220, v66, v224
	v_fma_f32 v179, v221, v67, v225
	v_fmac_f32_dpp v172, v76, v198 row_shr:1 row_mask:0xf bank_mask:0xf
	v_fmac_f32_dpp v173, v77, v199 row_shr:1 row_mask:0xf bank_mask:0xf
	v_fmac_f32_dpp v174, v78, v200 row_shr:1 row_mask:0xf bank_mask:0xf
	v_fmac_f32_dpp v175, v79, v201 row_shr:1 row_mask:0xf bank_mask:0xf
	v_fmac_f32_dpp v176, v64, v214 row_shr:1 row_mask:0xf bank_mask:0xf
	v_fmac_f32_dpp v177, v65, v215 row_shr:1 row_mask:0xf bank_mask:0xf
	v_fmac_f32_dpp v178, v66, v216 row_shr:1 row_mask:0xf bank_mask:0xf
	v_fmac_f32_dpp v179, v67, v217 row_shr:1 row_mask:0xf bank_mask:0xf
	v_fmac_f32_dpp v172, v76, v194 row_shr:2 row_mask:0xf bank_mask:0xf
	v_fmac_f32_dpp v173, v77, v195 row_shr:2 row_mask:0xf bank_mask:0xf
	v_fmac_f32_dpp v174, v78, v196 row_shr:2 row_mask:0xf bank_mask:0xf
	v_fmac_f32_dpp v175, v79, v197 row_shr:2 row_mask:0xf bank_mask:0xf
	v_fmac_f32_dpp v176, v64, v210 row_shr:2 row_mask:0xf bank_mask:0xf
	v_fmac_f32_dpp v177, v65, v211 row_shr:2 row_mask:0xf bank_mask:0xf
	v_fmac_f32_dpp v178, v66, v212 row_shr:2 row_mask:0xf bank_mask:0xf
	v_fmac_f32_dpp v179, v67, v213 row_shr:2 row_mask:0xf bank_mask:0xf
	v_fmac_f32_dpp v172, v92, v198 row_shl:15 row_mask:0xf bank_mask:0xf
	v_fmac_f32_dpp v173, v93, v199 row_shl:15 row_mask:0xf bank_mask:0xf
	v_fmac_f32_dpp v174, v94, v200 row_shl:15 row_mask:0xf bank_mask:0xf
	v_fmac_f32_dpp v175, v95, v201 row_shl:15 row_mask:0xf bank_mask:0xf
	v_fmac_f32_dpp v176, v72, v214 row_shl:15 row_mask:0xf bank_mask:0xf
	v_fmac_f32_dpp v177, v73, v215 row_shl:15 row_mask:0xf bank_mask:0xf
	v_fmac_f32_dpp v178, v74, v216 row_shl:15 row_mask:0xf bank_mask:0xf
	v_fmac_f32_dpp v179, v75, v217 row_shl:15 row_mask:0xf bank_mask:0xf
	v_fmac_f32_dpp v172, v92, v194 row_shl:14 row_mask:0xf bank_mask:0xf
	v_fmac_f32_dpp v173, v93, v195 row_shl:14 row_mask:0xf bank_mask:0xf
	v_fmac_f32_dpp v174, v94, v196 row_shl:14 row_mask:0xf bank_mask:0xf
	v_fmac_f32_dpp v175, v95, v197 row_shl:14 row_mask:0xf bank_mask:0xf
	v_fmac_f32_dpp v176, v72, v210 row_shl:14 row_mask:0xf bank_mask:0xf
	v_fmac_f32_dpp v177, v73, v211 row_shl:14 row_mask:0xf bank_mask:0xf
	v_fmac_f32_dpp v178, v74, v212 row_shl:14 row_mask:0xf bank_mask:0xf
	v_fmac_f32_dpp v179, v75, v213 row_shl:14 row_mask:0xf bank_mask:0xf
	v_mul_f32_e32 v180, 0x3d372713, v172
	v_mul_f32_e32 v181, 0x3d372713, v173
	v_mul_f32_e32 v182, 0x3d372713, v174
	v_mul_f32_e32 v183, 0x3d372713, v175
	v_mul_f32_e32 v180, v172, v180
	v_mul_f32_e32 v181, v173, v181
	v_mul_f32_e32 v182, v174, v182
	v_mul_f32_e32 v183, v175, v183
	v_fma_f32 v180, v172, v180, v172
	v_fma_f32 v181, v173, v181, v173
	v_fma_f32 v182, v174, v182, v174
	v_fma_f32 v183, v175, v183, v175
	v_mul_f32_e32 v180, 0xc0135761, v180
	v_mul_f32_e32 v181, 0xc0135761, v181
	v_mul_f32_e32 v182, 0xc0135761, v182
	v_mul_f32_e32 v183, 0xc0135761, v183
	v_exp_f32_e32 v180, v180
	v_exp_f32_e32 v181, v181
	v_exp_f32_e32 v182, v182
	v_exp_f32_e32 v183, v183
	v_add_f32_e32 v180, 1.0, v180
	v_add_f32_e32 v181, 1.0, v181
	v_add_f32_e32 v182, 1.0, v182
	v_add_f32_e32 v183, 1.0, v183
	v_rcp_f32_e32 v180, v180
	v_rcp_f32_e32 v181, v181
	v_rcp_f32_e32 v182, v182
	v_rcp_f32_e32 v183, v183
	v_mul_f32_e32 v172, v172, v180
	v_mul_f32_e32 v173, v173, v181
	v_mul_f32_e32 v174, v174, v182
	v_mul_f32_e32 v175, v175, v183
	v_mul_f32_e32 v172, v172, v176
	v_mul_f32_e32 v173, v173, v177
	v_mul_f32_e32 v174, v174, v178
	v_mul_f32_e32 v175, v175, v179
	v_cvt_pk_bf16_f32 v86, v172, v173
	v_cvt_pk_bf16_f32 v87, v174, v175
	v_add_u32_e32 v241, 0x42000, v235
	global_store_dwordx4 v241, v[84:87], s[56:57]
	v_fma_f32 v172, v202, v92, v206
	v_fma_f32 v173, v203, v93, v207
	v_fma_f32 v174, v204, v94, v208
	v_fma_f32 v175, v205, v95, v209
	v_fma_f32 v176, v218, v72, v222
	v_fma_f32 v177, v219, v73, v223
	v_fma_f32 v178, v220, v74, v224
	v_fma_f32 v179, v221, v75, v225
	v_fmac_f32_dpp v172, v92, v198 row_shr:1 row_mask:0xf bank_mask:0xf
	v_fmac_f32_dpp v173, v93, v199 row_shr:1 row_mask:0xf bank_mask:0xf
	v_fmac_f32_dpp v174, v94, v200 row_shr:1 row_mask:0xf bank_mask:0xf
	v_fmac_f32_dpp v175, v95, v201 row_shr:1 row_mask:0xf bank_mask:0xf
	v_fmac_f32_dpp v176, v72, v214 row_shr:1 row_mask:0xf bank_mask:0xf
	v_fmac_f32_dpp v177, v73, v215 row_shr:1 row_mask:0xf bank_mask:0xf
	v_fmac_f32_dpp v178, v74, v216 row_shr:1 row_mask:0xf bank_mask:0xf
	v_fmac_f32_dpp v179, v75, v217 row_shr:1 row_mask:0xf bank_mask:0xf
	v_fmac_f32_dpp v172, v92, v194 row_shr:2 row_mask:0xf bank_mask:0xf
	v_fmac_f32_dpp v173, v93, v195 row_shr:2 row_mask:0xf bank_mask:0xf
	v_fmac_f32_dpp v174, v94, v196 row_shr:2 row_mask:0xf bank_mask:0xf
	v_fmac_f32_dpp v175, v95, v197 row_shr:2 row_mask:0xf bank_mask:0xf
	v_fmac_f32_dpp v176, v72, v210 row_shr:2 row_mask:0xf bank_mask:0xf
	v_fmac_f32_dpp v177, v73, v211 row_shr:2 row_mask:0xf bank_mask:0xf
	v_fmac_f32_dpp v178, v74, v212 row_shr:2 row_mask:0xf bank_mask:0xf
	v_fmac_f32_dpp v179, v75, v213 row_shr:2 row_mask:0xf bank_mask:0xf
	v_fmac_f32_dpp v172, v108, v198 row_shl:15 row_mask:0xf bank_mask:0xf
	v_fmac_f32_dpp v173, v109, v199 row_shl:15 row_mask:0xf bank_mask:0xf
	v_fmac_f32_dpp v174, v110, v200 row_shl:15 row_mask:0xf bank_mask:0xf
	v_fmac_f32_dpp v175, v111, v201 row_shl:15 row_mask:0xf bank_mask:0xf
	v_fmac_f32_dpp v176, v88, v214 row_shl:15 row_mask:0xf bank_mask:0xf
	v_fmac_f32_dpp v177, v89, v215 row_shl:15 row_mask:0xf bank_mask:0xf
	v_fmac_f32_dpp v178, v90, v216 row_shl:15 row_mask:0xf bank_mask:0xf
	v_fmac_f32_dpp v179, v91, v217 row_shl:15 row_mask:0xf bank_mask:0xf
	v_fmac_f32_dpp v172, v108, v194 row_shl:14 row_mask:0xf bank_mask:0xf
	v_fmac_f32_dpp v173, v109, v195 row_shl:14 row_mask:0xf bank_mask:0xf
	v_fmac_f32_dpp v174, v110, v196 row_shl:14 row_mask:0xf bank_mask:0xf
	v_fmac_f32_dpp v175, v111, v197 row_shl:14 row_mask:0xf bank_mask:0xf
	v_fmac_f32_dpp v176, v88, v210 row_shl:14 row_mask:0xf bank_mask:0xf
	v_fmac_f32_dpp v177, v89, v211 row_shl:14 row_mask:0xf bank_mask:0xf
	v_fmac_f32_dpp v178, v90, v212 row_shl:14 row_mask:0xf bank_mask:0xf
	v_fmac_f32_dpp v179, v91, v213 row_shl:14 row_mask:0xf bank_mask:0xf
	v_mul_f32_e32 v180, 0x3d372713, v172
	v_mul_f32_e32 v181, 0x3d372713, v173
	v_mul_f32_e32 v182, 0x3d372713, v174
	v_mul_f32_e32 v183, 0x3d372713, v175
	v_mul_f32_e32 v180, v172, v180
	v_mul_f32_e32 v181, v173, v181
	v_mul_f32_e32 v182, v174, v182
	v_mul_f32_e32 v183, v175, v183
	v_fma_f32 v180, v172, v180, v172
	v_fma_f32 v181, v173, v181, v173
	v_fma_f32 v182, v174, v182, v174
	v_fma_f32 v183, v175, v183, v175
	v_mul_f32_e32 v180, 0xc0135761, v180
	v_mul_f32_e32 v181, 0xc0135761, v181
	v_mul_f32_e32 v182, 0xc0135761, v182
	v_mul_f32_e32 v183, 0xc0135761, v183
	v_exp_f32_e32 v180, v180
	v_exp_f32_e32 v181, v181
	v_exp_f32_e32 v182, v182
	v_exp_f32_e32 v183, v183
	v_add_f32_e32 v180, 1.0, v180
	v_add_f32_e32 v181, 1.0, v181
	v_add_f32_e32 v182, 1.0, v182
	v_add_f32_e32 v183, 1.0, v183
	v_rcp_f32_e32 v180, v180
	v_rcp_f32_e32 v181, v181
	v_rcp_f32_e32 v182, v182
	v_rcp_f32_e32 v183, v183
	v_mul_f32_e32 v172, v172, v180
	v_mul_f32_e32 v173, v173, v181
	v_mul_f32_e32 v174, v174, v182
	v_mul_f32_e32 v175, v175, v183
	v_mul_f32_e32 v172, v172, v176
	v_mul_f32_e32 v173, v173, v177
	v_mul_f32_e32 v174, v174, v178
	v_mul_f32_e32 v175, v175, v179
	v_cvt_pk_bf16_f32 v102, v172, v173
	v_cvt_pk_bf16_f32 v103, v174, v175
	v_add_u32_e32 v241, 0x2c000, v235
	global_store_dwordx4 v241, v[100:103], s[56:57]
	v_fma_f32 v172, v202, v108, v206
	v_fma_f32 v173, v203, v109, v207
	v_fma_f32 v174, v204, v110, v208
	v_fma_f32 v175, v205, v111, v209
	v_fma_f32 v176, v218, v88, v222
	v_fma_f32 v177, v219, v89, v223
	v_fma_f32 v178, v220, v90, v224
	v_fma_f32 v179, v221, v91, v225
	v_fmac_f32_dpp v172, v108, v198 row_shr:1 row_mask:0xf bank_mask:0xf
	v_fmac_f32_dpp v173, v109, v199 row_shr:1 row_mask:0xf bank_mask:0xf
	v_fmac_f32_dpp v174, v110, v200 row_shr:1 row_mask:0xf bank_mask:0xf
	v_fmac_f32_dpp v175, v111, v201 row_shr:1 row_mask:0xf bank_mask:0xf
	v_fmac_f32_dpp v176, v88, v214 row_shr:1 row_mask:0xf bank_mask:0xf
	v_fmac_f32_dpp v177, v89, v215 row_shr:1 row_mask:0xf bank_mask:0xf
	v_fmac_f32_dpp v178, v90, v216 row_shr:1 row_mask:0xf bank_mask:0xf
	v_fmac_f32_dpp v179, v91, v217 row_shr:1 row_mask:0xf bank_mask:0xf
	v_fmac_f32_dpp v172, v108, v194 row_shr:2 row_mask:0xf bank_mask:0xf
	v_fmac_f32_dpp v173, v109, v195 row_shr:2 row_mask:0xf bank_mask:0xf
	v_fmac_f32_dpp v174, v110, v196 row_shr:2 row_mask:0xf bank_mask:0xf
	v_fmac_f32_dpp v175, v111, v197 row_shr:2 row_mask:0xf bank_mask:0xf
	v_fmac_f32_dpp v176, v88, v210 row_shr:2 row_mask:0xf bank_mask:0xf
	v_fmac_f32_dpp v177, v89, v211 row_shr:2 row_mask:0xf bank_mask:0xf
	v_fmac_f32_dpp v178, v90, v212 row_shr:2 row_mask:0xf bank_mask:0xf
	v_fmac_f32_dpp v179, v91, v213 row_shr:2 row_mask:0xf bank_mask:0xf
	v_fmac_f32_dpp v172, v120, v198 row_shl:15 row_mask:0xf bank_mask:0xf
	v_fmac_f32_dpp v173, v121, v199 row_shl:15 row_mask:0xf bank_mask:0xf
	v_fmac_f32_dpp v174, v122, v200 row_shl:15 row_mask:0xf bank_mask:0xf
	v_fmac_f32_dpp v175, v123, v201 row_shl:15 row_mask:0xf bank_mask:0xf
	v_fmac_f32_dpp v176, v104, v214 row_shl:15 row_mask:0xf bank_mask:0xf
	v_fmac_f32_dpp v177, v105, v215 row_shl:15 row_mask:0xf bank_mask:0xf
	v_fmac_f32_dpp v178, v106, v216 row_shl:15 row_mask:0xf bank_mask:0xf
	v_fmac_f32_dpp v179, v107, v217 row_shl:15 row_mask:0xf bank_mask:0xf
	v_fmac_f32_dpp v172, v120, v194 row_shl:14 row_mask:0xf bank_mask:0xf
	v_fmac_f32_dpp v173, v121, v195 row_shl:14 row_mask:0xf bank_mask:0xf
	v_fmac_f32_dpp v174, v122, v196 row_shl:14 row_mask:0xf bank_mask:0xf
	v_fmac_f32_dpp v175, v123, v197 row_shl:14 row_mask:0xf bank_mask:0xf
	v_fmac_f32_dpp v176, v104, v210 row_shl:14 row_mask:0xf bank_mask:0xf
	v_fmac_f32_dpp v177, v105, v211 row_shl:14 row_mask:0xf bank_mask:0xf
	v_fmac_f32_dpp v178, v106, v212 row_shl:14 row_mask:0xf bank_mask:0xf
	v_fmac_f32_dpp v179, v107, v213 row_shl:14 row_mask:0xf bank_mask:0xf
	v_mul_f32_e32 v180, 0x3d372713, v172
	v_mul_f32_e32 v181, 0x3d372713, v173
	v_mul_f32_e32 v182, 0x3d372713, v174
	v_mul_f32_e32 v183, 0x3d372713, v175
	v_mul_f32_e32 v180, v172, v180
	v_mul_f32_e32 v181, v173, v181
	v_mul_f32_e32 v182, v174, v182
	v_mul_f32_e32 v183, v175, v183
	v_fma_f32 v180, v172, v180, v172
	v_fma_f32 v181, v173, v181, v173
	v_fma_f32 v182, v174, v182, v174
	v_fma_f32 v183, v175, v183, v175
	v_mul_f32_e32 v180, 0xc0135761, v180
	v_mul_f32_e32 v181, 0xc0135761, v181
	v_mul_f32_e32 v182, 0xc0135761, v182
	v_mul_f32_e32 v183, 0xc0135761, v183
	v_exp_f32_e32 v180, v180
	v_exp_f32_e32 v181, v181
	v_exp_f32_e32 v182, v182
	v_exp_f32_e32 v183, v183
	v_add_f32_e32 v180, 1.0, v180
	v_add_f32_e32 v181, 1.0, v181
	v_add_f32_e32 v182, 1.0, v182
	v_add_f32_e32 v183, 1.0, v183
	v_rcp_f32_e32 v180, v180
	v_rcp_f32_e32 v181, v181
	v_rcp_f32_e32 v182, v182
	v_rcp_f32_e32 v183, v183
	v_mul_f32_e32 v172, v172, v180
	v_mul_f32_e32 v173, v173, v181
	v_mul_f32_e32 v174, v174, v182
	v_mul_f32_e32 v175, v175, v183
	v_mul_f32_e32 v172, v172, v176
	v_mul_f32_e32 v173, v173, v177
	v_mul_f32_e32 v174, v174, v178
	v_mul_f32_e32 v175, v175, v179
	v_cvt_pk_bf16_f32 v114, v172, v173
	v_cvt_pk_bf16_f32 v115, v174, v175
	v_add_u32_e32 v241, 0x16000, v235
	global_store_dwordx4 v241, v[112:115], s[56:57]
	v_fma_f32 v172, v202, v120, v206
	v_fma_f32 v173, v203, v121, v207
	v_fma_f32 v174, v204, v122, v208
	v_fma_f32 v175, v205, v123, v209
	v_fma_f32 v176, v218, v104, v222
	v_fma_f32 v177, v219, v105, v223
	v_fma_f32 v178, v220, v106, v224
	v_fma_f32 v179, v221, v107, v225
	v_fmac_f32_dpp v172, v120, v198 row_shr:1 row_mask:0xf bank_mask:0xf
	v_fmac_f32_dpp v173, v121, v199 row_shr:1 row_mask:0xf bank_mask:0xf
	v_fmac_f32_dpp v174, v122, v200 row_shr:1 row_mask:0xf bank_mask:0xf
	v_fmac_f32_dpp v175, v123, v201 row_shr:1 row_mask:0xf bank_mask:0xf
	v_fmac_f32_dpp v176, v104, v214 row_shr:1 row_mask:0xf bank_mask:0xf
	v_fmac_f32_dpp v177, v105, v215 row_shr:1 row_mask:0xf bank_mask:0xf
	v_fmac_f32_dpp v178, v106, v216 row_shr:1 row_mask:0xf bank_mask:0xf
	v_fmac_f32_dpp v179, v107, v217 row_shr:1 row_mask:0xf bank_mask:0xf
	v_fmac_f32_dpp v172, v120, v194 row_shr:2 row_mask:0xf bank_mask:0xf
	v_fmac_f32_dpp v173, v121, v195 row_shr:2 row_mask:0xf bank_mask:0xf
	v_fmac_f32_dpp v174, v122, v196 row_shr:2 row_mask:0xf bank_mask:0xf
	v_fmac_f32_dpp v175, v123, v197 row_shr:2 row_mask:0xf bank_mask:0xf
	v_fmac_f32_dpp v176, v104, v210 row_shr:2 row_mask:0xf bank_mask:0xf
	v_fmac_f32_dpp v177, v105, v211 row_shr:2 row_mask:0xf bank_mask:0xf
	v_fmac_f32_dpp v178, v106, v212 row_shr:2 row_mask:0xf bank_mask:0xf
	v_fmac_f32_dpp v179, v107, v213 row_shr:2 row_mask:0xf bank_mask:0xf
	v_fmac_f32_dpp v172, v128, v198 row_shl:15 row_mask:0xf bank_mask:0xf
	v_fmac_f32_dpp v173, v129, v199 row_shl:15 row_mask:0xf bank_mask:0xf
	v_fmac_f32_dpp v174, v130, v200 row_shl:15 row_mask:0xf bank_mask:0xf
	v_fmac_f32_dpp v175, v131, v201 row_shl:15 row_mask:0xf bank_mask:0xf
	v_fmac_f32_dpp v176, v132, v214 row_shl:15 row_mask:0xf bank_mask:0xf
	v_fmac_f32_dpp v177, v133, v215 row_shl:15 row_mask:0xf bank_mask:0xf
	v_fmac_f32_dpp v178, v134, v216 row_shl:15 row_mask:0xf bank_mask:0xf
	v_fmac_f32_dpp v179, v135, v217 row_shl:15 row_mask:0xf bank_mask:0xf
	v_fmac_f32_dpp v172, v128, v194 row_shl:14 row_mask:0xf bank_mask:0xf
	v_fmac_f32_dpp v173, v129, v195 row_shl:14 row_mask:0xf bank_mask:0xf
	v_fmac_f32_dpp v174, v130, v196 row_shl:14 row_mask:0xf bank_mask:0xf
	v_fmac_f32_dpp v175, v131, v197 row_shl:14 row_mask:0xf bank_mask:0xf
	v_fmac_f32_dpp v176, v132, v210 row_shl:14 row_mask:0xf bank_mask:0xf
	v_fmac_f32_dpp v177, v133, v211 row_shl:14 row_mask:0xf bank_mask:0xf
	v_fmac_f32_dpp v178, v134, v212 row_shl:14 row_mask:0xf bank_mask:0xf
	v_fmac_f32_dpp v179, v135, v213 row_shl:14 row_mask:0xf bank_mask:0xf
	v_mul_f32_e32 v180, 0x3d372713, v172
	v_mul_f32_e32 v181, 0x3d372713, v173
	v_mul_f32_e32 v182, 0x3d372713, v174
	v_mul_f32_e32 v183, 0x3d372713, v175
	v_mul_f32_e32 v180, v172, v180
	v_mul_f32_e32 v181, v173, v181
	v_mul_f32_e32 v182, v174, v182
	v_mul_f32_e32 v183, v175, v183
	v_fma_f32 v180, v172, v180, v172
	v_fma_f32 v181, v173, v181, v173
	v_fma_f32 v182, v174, v182, v174
	v_fma_f32 v183, v175, v183, v175
	v_mul_f32_e32 v180, 0xc0135761, v180
	v_mul_f32_e32 v181, 0xc0135761, v181
	v_mul_f32_e32 v182, 0xc0135761, v182
	v_mul_f32_e32 v183, 0xc0135761, v183
	v_exp_f32_e32 v180, v180
	v_exp_f32_e32 v181, v181
	v_exp_f32_e32 v182, v182
	v_exp_f32_e32 v183, v183
	v_add_f32_e32 v180, 1.0, v180
	v_add_f32_e32 v181, 1.0, v181
	v_add_f32_e32 v182, 1.0, v182
	v_add_f32_e32 v183, 1.0, v183
	v_rcp_f32_e32 v180, v180
	v_rcp_f32_e32 v181, v181
	v_rcp_f32_e32 v182, v182
	v_rcp_f32_e32 v183, v183
	v_mul_f32_e32 v172, v172, v180
	v_mul_f32_e32 v173, v173, v181
	v_mul_f32_e32 v174, v174, v182
	v_mul_f32_e32 v175, v175, v183
	v_mul_f32_e32 v172, v172, v176
	v_mul_f32_e32 v173, v173, v177
	v_mul_f32_e32 v174, v174, v178
	v_mul_f32_e32 v175, v175, v179
	v_cvt_pk_bf16_f32 v126, v172, v173
	v_cvt_pk_bf16_f32 v127, v174, v175
	v_add_u32_e32 v241, 0x0, v235
	s_cmp_lg_u32 s33, 0
	s_cbranch_scc1 .Lepi9_wr1_3
	s_andn2_b64 exec, exec, s[52:53]
	global_store_dwordx4 v241, v[124:127], s[56:57]
	s_mov_b64 exec, -1
	s_branch .Lepi9_wrend_3
.Lepi9_wr1_3:
	global_store_dwordx4 v241, v[124:127], s[56:57]
.Lepi9_wrend_3:
	v_fma_f32 v172, v202, v12, v206
	v_fma_f32 v173, v203, v13, v207
	v_fma_f32 v174, v204, v14, v208
	v_fma_f32 v175, v205, v15, v209
	v_fma_f32 v176, v218, v0, v222
	v_fma_f32 v177, v219, v1, v223
	v_fma_f32 v178, v220, v2, v224
	v_fma_f32 v179, v221, v3, v225
	v_fmac_f32_dpp v172, v12, v198 row_shr:1 row_mask:0xf bank_mask:0xf
	v_fmac_f32_dpp v173, v13, v199 row_shr:1 row_mask:0xf bank_mask:0xf
	v_fmac_f32_dpp v174, v14, v200 row_shr:1 row_mask:0xf bank_mask:0xf
	v_fmac_f32_dpp v175, v15, v201 row_shr:1 row_mask:0xf bank_mask:0xf
	v_fmac_f32_dpp v176, v0, v214 row_shr:1 row_mask:0xf bank_mask:0xf
	v_fmac_f32_dpp v177, v1, v215 row_shr:1 row_mask:0xf bank_mask:0xf
	v_fmac_f32_dpp v178, v2, v216 row_shr:1 row_mask:0xf bank_mask:0xf
	v_fmac_f32_dpp v179, v3, v217 row_shr:1 row_mask:0xf bank_mask:0xf
	v_fmac_f32_dpp v172, v12, v194 row_shr:2 row_mask:0xf bank_mask:0xf
	v_fmac_f32_dpp v173, v13, v195 row_shr:2 row_mask:0xf bank_mask:0xf
	v_fmac_f32_dpp v174, v14, v196 row_shr:2 row_mask:0xf bank_mask:0xf
	v_fmac_f32_dpp v175, v15, v197 row_shr:2 row_mask:0xf bank_mask:0xf
	v_fmac_f32_dpp v176, v0, v210 row_shr:2 row_mask:0xf bank_mask:0xf
	v_fmac_f32_dpp v177, v1, v211 row_shr:2 row_mask:0xf bank_mask:0xf
	v_fmac_f32_dpp v178, v2, v212 row_shr:2 row_mask:0xf bank_mask:0xf
	v_fmac_f32_dpp v179, v3, v213 row_shr:2 row_mask:0xf bank_mask:0xf
	v_fmac_f32_dpp v172, v28, v198 row_shl:15 row_mask:0xf bank_mask:0xf
	v_fmac_f32_dpp v173, v29, v199 row_shl:15 row_mask:0xf bank_mask:0xf
	v_fmac_f32_dpp v174, v30, v200 row_shl:15 row_mask:0xf bank_mask:0xf
	v_fmac_f32_dpp v175, v31, v201 row_shl:15 row_mask:0xf bank_mask:0xf
	v_fmac_f32_dpp v176, v8, v214 row_shl:15 row_mask:0xf bank_mask:0xf
	v_fmac_f32_dpp v177, v9, v215 row_shl:15 row_mask:0xf bank_mask:0xf
	v_fmac_f32_dpp v178, v10, v216 row_shl:15 row_mask:0xf bank_mask:0xf
	v_fmac_f32_dpp v179, v11, v217 row_shl:15 row_mask:0xf bank_mask:0xf
	v_fmac_f32_dpp v172, v28, v194 row_shl:14 row_mask:0xf bank_mask:0xf
	v_fmac_f32_dpp v173, v29, v195 row_shl:14 row_mask:0xf bank_mask:0xf
	v_fmac_f32_dpp v174, v30, v196 row_shl:14 row_mask:0xf bank_mask:0xf
	v_fmac_f32_dpp v175, v31, v197 row_shl:14 row_mask:0xf bank_mask:0xf
	v_fmac_f32_dpp v176, v8, v210 row_shl:14 row_mask:0xf bank_mask:0xf
	v_fmac_f32_dpp v177, v9, v211 row_shl:14 row_mask:0xf bank_mask:0xf
	v_fmac_f32_dpp v178, v10, v212 row_shl:14 row_mask:0xf bank_mask:0xf
	v_fmac_f32_dpp v179, v11, v213 row_shl:14 row_mask:0xf bank_mask:0xf
	v_mul_f32_e32 v180, 0x3d372713, v172
	v_mul_f32_e32 v181, 0x3d372713, v173
	v_mul_f32_e32 v182, 0x3d372713, v174
	v_mul_f32_e32 v183, 0x3d372713, v175
	v_mul_f32_e32 v180, v172, v180
	v_mul_f32_e32 v181, v173, v181
	v_mul_f32_e32 v182, v174, v182
	v_mul_f32_e32 v183, v175, v183
	v_fma_f32 v180, v172, v180, v172
	v_fma_f32 v181, v173, v181, v173
	v_fma_f32 v182, v174, v182, v174
	v_fma_f32 v183, v175, v183, v175
	v_mul_f32_e32 v180, 0xc0135761, v180
	v_mul_f32_e32 v181, 0xc0135761, v181
	v_mul_f32_e32 v182, 0xc0135761, v182
	v_mul_f32_e32 v183, 0xc0135761, v183
	v_exp_f32_e32 v180, v180
	v_exp_f32_e32 v181, v181
	v_exp_f32_e32 v182, v182
	v_exp_f32_e32 v183, v183
	v_add_f32_e32 v180, 1.0, v180
	v_add_f32_e32 v181, 1.0, v181
	v_add_f32_e32 v182, 1.0, v182
	v_add_f32_e32 v183, 1.0, v183
	v_rcp_f32_e32 v180, v180
	v_rcp_f32_e32 v181, v181
	v_rcp_f32_e32 v182, v182
	v_rcp_f32_e32 v183, v183
	v_mul_f32_e32 v172, v172, v180
	v_mul_f32_e32 v173, v173, v181
	v_mul_f32_e32 v174, v174, v182
	v_mul_f32_e32 v175, v175, v183
	v_mul_f32_e32 v172, v172, v176
	v_mul_f32_e32 v173, v173, v177
	v_mul_f32_e32 v174, v174, v178
	v_mul_f32_e32 v175, v175, v179
	v_cvt_pk_bf16_f32 v22, v172, v173
	v_cvt_pk_bf16_f32 v23, v174, v175
	v_add_u32_e32 v241, 0xf2000, v235
	global_store_dwordx4 v241, v[20:23], s[56:57]
	v_fma_f32 v172, v202, v28, v206
	v_fma_f32 v173, v203, v29, v207
	v_fma_f32 v174, v204, v30, v208
	v_fma_f32 v175, v205, v31, v209
	v_fma_f32 v176, v218, v8, v222
	v_fma_f32 v177, v219, v9, v223
	v_fma_f32 v178, v220, v10, v224
	v_fma_f32 v179, v221, v11, v225
	v_fmac_f32_dpp v172, v28, v198 row_shr:1 row_mask:0xf bank_mask:0xf
	v_fmac_f32_dpp v173, v29, v199 row_shr:1 row_mask:0xf bank_mask:0xf
	v_fmac_f32_dpp v174, v30, v200 row_shr:1 row_mask:0xf bank_mask:0xf
	v_fmac_f32_dpp v175, v31, v201 row_shr:1 row_mask:0xf bank_mask:0xf
	v_fmac_f32_dpp v176, v8, v214 row_shr:1 row_mask:0xf bank_mask:0xf
	v_fmac_f32_dpp v177, v9, v215 row_shr:1 row_mask:0xf bank_mask:0xf
	v_fmac_f32_dpp v178, v10, v216 row_shr:1 row_mask:0xf bank_mask:0xf
	v_fmac_f32_dpp v179, v11, v217 row_shr:1 row_mask:0xf bank_mask:0xf
	v_fmac_f32_dpp v172, v28, v194 row_shr:2 row_mask:0xf bank_mask:0xf
	v_fmac_f32_dpp v173, v29, v195 row_shr:2 row_mask:0xf bank_mask:0xf
	v_fmac_f32_dpp v174, v30, v196 row_shr:2 row_mask:0xf bank_mask:0xf
	v_fmac_f32_dpp v175, v31, v197 row_shr:2 row_mask:0xf bank_mask:0xf
	v_fmac_f32_dpp v176, v8, v210 row_shr:2 row_mask:0xf bank_mask:0xf
	v_fmac_f32_dpp v177, v9, v211 row_shr:2 row_mask:0xf bank_mask:0xf
	v_fmac_f32_dpp v178, v10, v212 row_shr:2 row_mask:0xf bank_mask:0xf
	v_fmac_f32_dpp v179, v11, v213 row_shr:2 row_mask:0xf bank_mask:0xf
	v_fmac_f32_dpp v172, v44, v198 row_shl:15 row_mask:0xf bank_mask:0xf
	v_fmac_f32_dpp v173, v45, v199 row_shl:15 row_mask:0xf bank_mask:0xf
	v_fmac_f32_dpp v174, v46, v200 row_shl:15 row_mask:0xf bank_mask:0xf
	v_fmac_f32_dpp v175, v47, v201 row_shl:15 row_mask:0xf bank_mask:0xf
	v_fmac_f32_dpp v176, v24, v214 row_shl:15 row_mask:0xf bank_mask:0xf
	v_fmac_f32_dpp v177, v25, v215 row_shl:15 row_mask:0xf bank_mask:0xf
	v_fmac_f32_dpp v178, v26, v216 row_shl:15 row_mask:0xf bank_mask:0xf
	v_fmac_f32_dpp v179, v27, v217 row_shl:15 row_mask:0xf bank_mask:0xf
	v_fmac_f32_dpp v172, v44, v194 row_shl:14 row_mask:0xf bank_mask:0xf
	v_fmac_f32_dpp v173, v45, v195 row_shl:14 row_mask:0xf bank_mask:0xf
	v_fmac_f32_dpp v174, v46, v196 row_shl:14 row_mask:0xf bank_mask:0xf
	v_fmac_f32_dpp v175, v47, v197 row_shl:14 row_mask:0xf bank_mask:0xf
	v_fmac_f32_dpp v176, v24, v210 row_shl:14 row_mask:0xf bank_mask:0xf
	v_fmac_f32_dpp v177, v25, v211 row_shl:14 row_mask:0xf bank_mask:0xf
	v_fmac_f32_dpp v178, v26, v212 row_shl:14 row_mask:0xf bank_mask:0xf
	v_fmac_f32_dpp v179, v27, v213 row_shl:14 row_mask:0xf bank_mask:0xf
	v_mul_f32_e32 v180, 0x3d372713, v172
	v_mul_f32_e32 v181, 0x3d372713, v173
	v_mul_f32_e32 v182, 0x3d372713, v174
	v_mul_f32_e32 v183, 0x3d372713, v175
	v_mul_f32_e32 v180, v172, v180
	v_mul_f32_e32 v181, v173, v181
	v_mul_f32_e32 v182, v174, v182
	v_mul_f32_e32 v183, v175, v183
	v_fma_f32 v180, v172, v180, v172
	v_fma_f32 v181, v173, v181, v173
	v_fma_f32 v182, v174, v182, v174
	v_fma_f32 v183, v175, v183, v175
	v_mul_f32_e32 v180, 0xc0135761, v180
	v_mul_f32_e32 v181, 0xc0135761, v181
	v_mul_f32_e32 v182, 0xc0135761, v182
	v_mul_f32_e32 v183, 0xc0135761, v183
	v_exp_f32_e32 v180, v180
	v_exp_f32_e32 v181, v181
	v_exp_f32_e32 v182, v182
	v_exp_f32_e32 v183, v183
	v_add_f32_e32 v180, 1.0, v180
	v_add_f32_e32 v181, 1.0, v181
	v_add_f32_e32 v182, 1.0, v182
	v_add_f32_e32 v183, 1.0, v183
	v_rcp_f32_e32 v180, v180
	v_rcp_f32_e32 v181, v181
	v_rcp_f32_e32 v182, v182
	v_rcp_f32_e32 v183, v183
	v_mul_f32_e32 v172, v172, v180
	v_mul_f32_e32 v173, v173, v181
	v_mul_f32_e32 v174, v174, v182
	v_mul_f32_e32 v175, v175, v183
	v_mul_f32_e32 v172, v172, v176
	v_mul_f32_e32 v173, v173, v177
	v_mul_f32_e32 v174, v174, v178
	v_mul_f32_e32 v175, v175, v179
	v_cvt_pk_bf16_f32 v38, v172, v173
	v_cvt_pk_bf16_f32 v39, v174, v175
	v_add_u32_e32 v241, 0xdc000, v235
	global_store_dwordx4 v241, v[36:39], s[56:57]
	v_fma_f32 v172, v202, v44, v206
	v_fma_f32 v173, v203, v45, v207
	v_fma_f32 v174, v204, v46, v208
	v_fma_f32 v175, v205, v47, v209
	v_fma_f32 v176, v218, v24, v222
	v_fma_f32 v177, v219, v25, v223
	v_fma_f32 v178, v220, v26, v224
	v_fma_f32 v179, v221, v27, v225
	v_fmac_f32_dpp v172, v44, v198 row_shr:1 row_mask:0xf bank_mask:0xf
	v_fmac_f32_dpp v173, v45, v199 row_shr:1 row_mask:0xf bank_mask:0xf
	v_fmac_f32_dpp v174, v46, v200 row_shr:1 row_mask:0xf bank_mask:0xf
	v_fmac_f32_dpp v175, v47, v201 row_shr:1 row_mask:0xf bank_mask:0xf
	v_fmac_f32_dpp v176, v24, v214 row_shr:1 row_mask:0xf bank_mask:0xf
	v_fmac_f32_dpp v177, v25, v215 row_shr:1 row_mask:0xf bank_mask:0xf
	v_fmac_f32_dpp v178, v26, v216 row_shr:1 row_mask:0xf bank_mask:0xf
	v_fmac_f32_dpp v179, v27, v217 row_shr:1 row_mask:0xf bank_mask:0xf
	v_fmac_f32_dpp v172, v44, v194 row_shr:2 row_mask:0xf bank_mask:0xf
	v_fmac_f32_dpp v173, v45, v195 row_shr:2 row_mask:0xf bank_mask:0xf
	v_fmac_f32_dpp v174, v46, v196 row_shr:2 row_mask:0xf bank_mask:0xf
	v_fmac_f32_dpp v175, v47, v197 row_shr:2 row_mask:0xf bank_mask:0xf
	v_fmac_f32_dpp v176, v24, v210 row_shr:2 row_mask:0xf bank_mask:0xf
	v_fmac_f32_dpp v177, v25, v211 row_shr:2 row_mask:0xf bank_mask:0xf
	v_fmac_f32_dpp v178, v26, v212 row_shr:2 row_mask:0xf bank_mask:0xf
	v_fmac_f32_dpp v179, v27, v213 row_shr:2 row_mask:0xf bank_mask:0xf
	v_fmac_f32_dpp v172, v56, v198 row_shl:15 row_mask:0xf bank_mask:0xf
	v_fmac_f32_dpp v173, v57, v199 row_shl:15 row_mask:0xf bank_mask:0xf
	v_fmac_f32_dpp v174, v58, v200 row_shl:15 row_mask:0xf bank_mask:0xf
	v_fmac_f32_dpp v175, v59, v201 row_shl:15 row_mask:0xf bank_mask:0xf
	v_fmac_f32_dpp v176, v40, v214 row_shl:15 row_mask:0xf bank_mask:0xf
	v_fmac_f32_dpp v177, v41, v215 row_shl:15 row_mask:0xf bank_mask:0xf
	v_fmac_f32_dpp v178, v42, v216 row_shl:15 row_mask:0xf bank_mask:0xf
	v_fmac_f32_dpp v179, v43, v217 row_shl:15 row_mask:0xf bank_mask:0xf
	v_fmac_f32_dpp v172, v56, v194 row_shl:14 row_mask:0xf bank_mask:0xf
	v_fmac_f32_dpp v173, v57, v195 row_shl:14 row_mask:0xf bank_mask:0xf
	v_fmac_f32_dpp v174, v58, v196 row_shl:14 row_mask:0xf bank_mask:0xf
	v_fmac_f32_dpp v175, v59, v197 row_shl:14 row_mask:0xf bank_mask:0xf
	v_fmac_f32_dpp v176, v40, v210 row_shl:14 row_mask:0xf bank_mask:0xf
	v_fmac_f32_dpp v177, v41, v211 row_shl:14 row_mask:0xf bank_mask:0xf
	v_fmac_f32_dpp v178, v42, v212 row_shl:14 row_mask:0xf bank_mask:0xf
	v_fmac_f32_dpp v179, v43, v213 row_shl:14 row_mask:0xf bank_mask:0xf
	v_mul_f32_e32 v180, 0x3d372713, v172
	v_mul_f32_e32 v181, 0x3d372713, v173
	v_mul_f32_e32 v182, 0x3d372713, v174
	v_mul_f32_e32 v183, 0x3d372713, v175
	v_mul_f32_e32 v180, v172, v180
	v_mul_f32_e32 v181, v173, v181
	v_mul_f32_e32 v182, v174, v182
	v_mul_f32_e32 v183, v175, v183
	v_fma_f32 v180, v172, v180, v172
	v_fma_f32 v181, v173, v181, v173
	v_fma_f32 v182, v174, v182, v174
	v_fma_f32 v183, v175, v183, v175
	v_mul_f32_e32 v180, 0xc0135761, v180
	v_mul_f32_e32 v181, 0xc0135761, v181
	v_mul_f32_e32 v182, 0xc0135761, v182
	v_mul_f32_e32 v183, 0xc0135761, v183
	v_exp_f32_e32 v180, v180
	v_exp_f32_e32 v181, v181
	v_exp_f32_e32 v182, v182
	v_exp_f32_e32 v183, v183
	v_add_f32_e32 v180, 1.0, v180
	v_add_f32_e32 v181, 1.0, v181
	v_add_f32_e32 v182, 1.0, v182
	v_add_f32_e32 v183, 1.0, v183
	v_rcp_f32_e32 v180, v180
	v_rcp_f32_e32 v181, v181
	v_rcp_f32_e32 v182, v182
	v_rcp_f32_e32 v183, v183
	v_mul_f32_e32 v172, v172, v180
	v_mul_f32_e32 v173, v173, v181
	v_mul_f32_e32 v174, v174, v182
	v_mul_f32_e32 v175, v175, v183
	v_mul_f32_e32 v172, v172, v176
	v_mul_f32_e32 v173, v173, v177
	v_mul_f32_e32 v174, v174, v178
	v_mul_f32_e32 v175, v175, v179
	v_cvt_pk_bf16_f32 v54, v172, v173
	v_cvt_pk_bf16_f32 v55, v174, v175
	v_add_u32_e32 v241, 0xc6000, v235
	global_store_dwordx4 v241, v[52:55], s[56:57]
	v_fma_f32 v172, v202, v56, v206
	v_fma_f32 v173, v203, v57, v207
	v_fma_f32 v174, v204, v58, v208
	v_fma_f32 v175, v205, v59, v209
	v_fma_f32 v176, v218, v40, v222
	v_fma_f32 v177, v219, v41, v223
	v_fma_f32 v178, v220, v42, v224
	v_fma_f32 v179, v221, v43, v225
	v_fmac_f32_dpp v172, v56, v198 row_shr:1 row_mask:0xf bank_mask:0xf
	v_fmac_f32_dpp v173, v57, v199 row_shr:1 row_mask:0xf bank_mask:0xf
	v_fmac_f32_dpp v174, v58, v200 row_shr:1 row_mask:0xf bank_mask:0xf
	v_fmac_f32_dpp v175, v59, v201 row_shr:1 row_mask:0xf bank_mask:0xf
	v_fmac_f32_dpp v176, v40, v214 row_shr:1 row_mask:0xf bank_mask:0xf
	v_fmac_f32_dpp v177, v41, v215 row_shr:1 row_mask:0xf bank_mask:0xf
	v_fmac_f32_dpp v178, v42, v216 row_shr:1 row_mask:0xf bank_mask:0xf
	v_fmac_f32_dpp v179, v43, v217 row_shr:1 row_mask:0xf bank_mask:0xf
	v_fmac_f32_dpp v172, v56, v194 row_shr:2 row_mask:0xf bank_mask:0xf
	v_fmac_f32_dpp v173, v57, v195 row_shr:2 row_mask:0xf bank_mask:0xf
	v_fmac_f32_dpp v174, v58, v196 row_shr:2 row_mask:0xf bank_mask:0xf
	v_fmac_f32_dpp v175, v59, v197 row_shr:2 row_mask:0xf bank_mask:0xf
	v_fmac_f32_dpp v176, v40, v210 row_shr:2 row_mask:0xf bank_mask:0xf
	v_fmac_f32_dpp v177, v41, v211 row_shr:2 row_mask:0xf bank_mask:0xf
	v_fmac_f32_dpp v178, v42, v212 row_shr:2 row_mask:0xf bank_mask:0xf
	v_fmac_f32_dpp v179, v43, v213 row_shr:2 row_mask:0xf bank_mask:0xf
	v_fmac_f32_dpp v172, v136, v198 row_shl:15 row_mask:0xf bank_mask:0xf
	v_fmac_f32_dpp v173, v137, v199 row_shl:15 row_mask:0xf bank_mask:0xf
	v_fmac_f32_dpp v174, v138, v200 row_shl:15 row_mask:0xf bank_mask:0xf
	v_fmac_f32_dpp v175, v139, v201 row_shl:15 row_mask:0xf bank_mask:0xf
	v_fmac_f32_dpp v176, v140, v214 row_shl:15 row_mask:0xf bank_mask:0xf
	v_fmac_f32_dpp v177, v141, v215 row_shl:15 row_mask:0xf bank_mask:0xf
	v_fmac_f32_dpp v178, v142, v216 row_shl:15 row_mask:0xf bank_mask:0xf
	v_fmac_f32_dpp v179, v143, v217 row_shl:15 row_mask:0xf bank_mask:0xf
	v_fmac_f32_dpp v172, v136, v194 row_shl:14 row_mask:0xf bank_mask:0xf
	v_fmac_f32_dpp v173, v137, v195 row_shl:14 row_mask:0xf bank_mask:0xf
	v_fmac_f32_dpp v174, v138, v196 row_shl:14 row_mask:0xf bank_mask:0xf
	v_fmac_f32_dpp v175, v139, v197 row_shl:14 row_mask:0xf bank_mask:0xf
	v_fmac_f32_dpp v176, v140, v210 row_shl:14 row_mask:0xf bank_mask:0xf
	v_fmac_f32_dpp v177, v141, v211 row_shl:14 row_mask:0xf bank_mask:0xf
	v_fmac_f32_dpp v178, v142, v212 row_shl:14 row_mask:0xf bank_mask:0xf
	v_fmac_f32_dpp v179, v143, v213 row_shl:14 row_mask:0xf bank_mask:0xf
	v_mul_f32_e32 v180, 0x3d372713, v172
	v_mul_f32_e32 v181, 0x3d372713, v173
	v_mul_f32_e32 v182, 0x3d372713, v174
	v_mul_f32_e32 v183, 0x3d372713, v175
	v_mul_f32_e32 v180, v172, v180
	v_mul_f32_e32 v181, v173, v181
	v_mul_f32_e32 v182, v174, v182
	v_mul_f32_e32 v183, v175, v183
	v_fma_f32 v180, v172, v180, v172
	v_fma_f32 v181, v173, v181, v173
	v_fma_f32 v182, v174, v182, v174
	v_fma_f32 v183, v175, v183, v175
	v_mul_f32_e32 v180, 0xc0135761, v180
	v_mul_f32_e32 v181, 0xc0135761, v181
	v_mul_f32_e32 v182, 0xc0135761, v182
	v_mul_f32_e32 v183, 0xc0135761, v183
	v_exp_f32_e32 v180, v180
	v_exp_f32_e32 v181, v181
	v_exp_f32_e32 v182, v182
	v_exp_f32_e32 v183, v183
	v_add_f32_e32 v180, 1.0, v180
	v_add_f32_e32 v181, 1.0, v181
	v_add_f32_e32 v182, 1.0, v182
	v_add_f32_e32 v183, 1.0, v183
	v_rcp_f32_e32 v180, v180
	v_rcp_f32_e32 v181, v181
	v_rcp_f32_e32 v182, v182
	v_rcp_f32_e32 v183, v183
	v_mul_f32_e32 v172, v172, v180
	v_mul_f32_e32 v173, v173, v181
	v_mul_f32_e32 v174, v174, v182
	v_mul_f32_e32 v175, v175, v183
	v_mul_f32_e32 v172, v172, v176
	v_mul_f32_e32 v173, v173, v177
	v_mul_f32_e32 v174, v174, v178
	v_mul_f32_e32 v175, v175, v179
	v_cvt_pk_bf16_f32 v62, v172, v173
	v_cvt_pk_bf16_f32 v63, v174, v175
	v_add_u32_e32 v241, 0xb0000, v235
	global_store_dwordx4 v241, v[60:63], s[56:57]
	s_branch .LBB0_1200
